# v097 + nt on split-K slab stores/loads and P10 query-fragment loads
# baseline (speedup 1.0000x reference)
.LBB0_444:
	v_lshl_add_u32 v148, s10, 8, v1
	v_lshl_or_b32 v146, s54, 8, v151
	s_mov_b64 s[36:37], -1
	s_cmp_gt_i32 s82, -1
	v_cvt_pk_bf16_f32 v66, v66, v67
	v_cvt_pk_bf16_f32 v67, v68, v69
	v_cvt_pk_bf16_f32 v68, v126, v127
	v_cvt_pk_bf16_f32 v69, v128, v129
	v_cvt_pk_bf16_f32 v62, v62, v63
	v_cvt_pk_bf16_f32 v63, v64, v65
	v_cvt_pk_bf16_f32 v64, v58, v59
	v_cvt_pk_bf16_f32 v65, v60, v61
	v_cvt_pk_bf16_f32 v58, v122, v123
	v_cvt_pk_bf16_f32 v59, v124, v125
	v_cvt_pk_bf16_f32 v60, v118, v119
	v_cvt_pk_bf16_f32 v61, v120, v121
	v_cvt_pk_bf16_f32 v54, v54, v55
	v_cvt_pk_bf16_f32 v55, v56, v57
	v_cvt_pk_bf16_f32 v56, v50, v51
	v_cvt_pk_bf16_f32 v57, v52, v53
	v_cvt_pk_bf16_f32 v50, v114, v115
	v_cvt_pk_bf16_f32 v51, v116, v117
	v_cvt_pk_bf16_f32 v52, v110, v111
	v_cvt_pk_bf16_f32 v53, v112, v113
	v_cvt_pk_bf16_f32 v46, v46, v47
	v_cvt_pk_bf16_f32 v47, v48, v49
	v_cvt_pk_bf16_f32 v48, v42, v43
	v_cvt_pk_bf16_f32 v49, v44, v45
	v_cvt_pk_bf16_f32 v42, v106, v107
	v_cvt_pk_bf16_f32 v43, v108, v109
	v_cvt_pk_bf16_f32 v44, v102, v103
	v_cvt_pk_bf16_f32 v45, v104, v105
	v_cvt_pk_bf16_f32 v38, v38, v39
	v_cvt_pk_bf16_f32 v39, v40, v41
	v_cvt_pk_bf16_f32 v40, v98, v99
	v_cvt_pk_bf16_f32 v41, v100, v101
	v_cvt_pk_bf16_f32 v34, v34, v35
	v_cvt_pk_bf16_f32 v35, v36, v37
	v_cvt_pk_bf16_f32 v36, v94, v95
	v_cvt_pk_bf16_f32 v37, v96, v97
	v_cvt_pk_bf16_f32 v30, v30, v31
	v_cvt_pk_bf16_f32 v31, v32, v33
	v_cvt_pk_bf16_f32 v32, v26, v27
	v_cvt_pk_bf16_f32 v33, v28, v29
	v_cvt_pk_bf16_f32 v26, v90, v91
	v_cvt_pk_bf16_f32 v27, v92, v93
	v_cvt_pk_bf16_f32 v28, v86, v87
	v_cvt_pk_bf16_f32 v29, v88, v89
	v_cvt_pk_bf16_f32 v22, v22, v23
	v_cvt_pk_bf16_f32 v23, v24, v25
	v_cvt_pk_bf16_f32 v24, v18, v19
	v_cvt_pk_bf16_f32 v25, v20, v21
	v_cvt_pk_bf16_f32 v18, v82, v83
	v_cvt_pk_bf16_f32 v19, v84, v85
	v_cvt_pk_bf16_f32 v20, v78, v79
	v_cvt_pk_bf16_f32 v21, v80, v81
	v_cvt_pk_bf16_f32 v14, v14, v15
	v_cvt_pk_bf16_f32 v15, v16, v17
	v_cvt_pk_bf16_f32 v16, v10, v11
	v_cvt_pk_bf16_f32 v17, v12, v13
	v_cvt_pk_bf16_f32 v10, v74, v75
	v_cvt_pk_bf16_f32 v11, v76, v77
	v_cvt_pk_bf16_f32 v12, v70, v71
	v_cvt_pk_bf16_f32 v13, v72, v73
	s_cbranch_scc0 .LBB0_458
	s_lshl_b32 s36, s52, 3
	s_add_i32 s46, s36, s82
	s_ashr_i32 s47, s46, 31
	s_lshl_b64 s[46:47], s[46:47], 17
	v_lshl_add_u64 v[74:75], v[138:139], 0, s[46:47]
	s_movk_i32 s10, 0x2000
	v_add_co_u32_e32 v70, vcc, s10, v74
	s_movk_i32 s10, 0x4000
	s_nop 0
	v_addc_co_u32_e32 v71, vcc, 0, v75, vcc
	global_store_dwordx4 v[70:71], v[62:65], off nt
	v_add_co_u32_e32 v70, vcc, s10, v74
	s_movk_i32 s10, 0x6000
	s_nop 0
	v_addc_co_u32_e32 v71, vcc, 0, v75, vcc
	global_store_dwordx4 v[70:71], v[58:61], off nt
	v_add_co_u32_e32 v70, vcc, s10, v74
	s_mov_b32 s10, 0x8000
	s_nop 0
	v_addc_co_u32_e32 v71, vcc, 0, v75, vcc
	global_store_dwordx4 v[70:71], v[54:57], off nt
	v_add_co_u32_e32 v70, vcc, s10, v74
	s_mov_b32 s10, 0xa000
	s_nop 0
	v_addc_co_u32_e32 v71, vcc, 0, v75, vcc
	global_store_dwordx4 v[70:71], v[50:53], off nt
	v_add_co_u32_e32 v70, vcc, s10, v74
	s_mov_b32 s10, 0xc000
	s_nop 0
	v_addc_co_u32_e32 v71, vcc, 0, v75, vcc
	global_store_dwordx4 v[70:71], v[46:49], off nt
	v_add_co_u32_e32 v70, vcc, s10, v74
	s_mov_b32 s10, 0xe000
	s_nop 0
	v_addc_co_u32_e32 v71, vcc, 0, v75, vcc
	global_store_dwordx4 v[70:71], v[42:45], off nt
	v_add_co_u32_e32 v70, vcc, s10, v74
	s_mov_b32 s10, 0x10000
	s_nop 0
	v_addc_co_u32_e32 v71, vcc, 0, v75, vcc
	global_store_dwordx4 v[70:71], v[38:41], off nt
	v_add_co_u32_e32 v70, vcc, s10, v74
	s_mov_b32 s10, 0x12000
	s_nop 0
	v_addc_co_u32_e32 v71, vcc, 0, v75, vcc
	global_store_dwordx4 v[70:71], v[34:37], off nt
	v_add_co_u32_e32 v70, vcc, s10, v74
	s_mov_b32 s10, 0x14000
	s_nop 0
	v_addc_co_u32_e32 v71, vcc, 0, v75, vcc
	global_store_dwordx4 v[70:71], v[30:33], off nt
	v_add_co_u32_e32 v70, vcc, s10, v74
	s_mov_b32 s10, 0x16000
	s_nop 0
	v_addc_co_u32_e32 v71, vcc, 0, v75, vcc
	global_store_dwordx4 v[70:71], v[26:29], off nt
	v_add_co_u32_e32 v70, vcc, s10, v74
	s_mov_b32 s10, 0x18000
	s_nop 0
	v_addc_co_u32_e32 v71, vcc, 0, v75, vcc
	global_store_dwordx4 v[70:71], v[22:25], off nt
	v_add_co_u32_e32 v70, vcc, s10, v74
	s_mov_b32 s10, 0x1a000
	s_nop 0
	v_addc_co_u32_e32 v71, vcc, 0, v75, vcc
	global_store_dwordx4 v[70:71], v[18:21], off nt
	v_add_co_u32_e32 v70, vcc, s10, v74
	s_mov_b32 s10, 0x1c000
	s_nop 0
	v_addc_co_u32_e32 v71, vcc, 0, v75, vcc
	global_store_dwordx4 v[70:71], v[14:17], off nt
	v_add_co_u32_e32 v70, vcc, s10, v74
	global_store_dwordx4 v[74:75], v[66:69], off nt
	s_nop 0
	v_addc_co_u32_e32 v71, vcc, 0, v75, vcc
	v_add_co_u32_e32 v74, vcc, 0x1e000, v74
	global_store_dwordx4 v[70:71], v[10:13], off nt
	v_cvt_pk_bf16_f32 v70, v6, v7
	v_cvt_pk_bf16_f32 v71, v8, v9
	v_cvt_pk_bf16_f32 v72, v2, v3
	v_cvt_pk_bf16_f32 v73, v4, v5
	v_addc_co_u32_e32 v75, vcc, 0, v75, vcc
	global_store_dwordx4 v[74:75], v[70:73], off nt
	s_waitcnt vmcnt(0)
	s_waitcnt vmcnt(0)
	s_barrier
	s_and_saveexec_b64 s[46:47], s[0:1]
	s_cbranch_execz .LBB0_457
	s_lshl_b32 s52, s52, 6
	s_mov_b64 s[54:55], exec
	s_ashr_i32 s53, s52, 31
	s_lshl_b64 s[52:53], s[52:53], 2
	buffer_wbl2 sc1
	s_waitcnt vmcnt(0)
	v_mbcnt_lo_u32_b32 v70, s54, 0
	s_add_u32 s52, s62, s52
	v_mbcnt_hi_u32_b32 v70, s55, v70
	s_addc_u32 s53, s63, s53
	v_cmp_eq_u32_e32 vcc, 0, v70
	s_and_saveexec_b64 s[58:59], vcc
	s_cbranch_execz .LBB0_448
	s_bcnt1_i32_b64 s10, s[54:55]
	v_mov_b32_e32 v70, s10
	global_atomic_add v133, v70, s[52:53]

.LBB0_457:
	s_or_b64 exec, exec, s[46:47]
	s_ashr_i32 s37, s36, 31
	s_lshl_b64 s[36:37], s[36:37], 17
	s_lshl_b32 s10, s82, 1
	v_lshl_add_u64 v[70:71], v[138:139], 0, s[36:37]
	s_lshl_b64 s[36:37], s[10:11], 13
	v_lshl_add_u64 v[70:71], v[70:71], 0, s[36:37]
	v_add_co_u32_e32 v72, vcc, 0x2000, v70
	s_nop 1
	v_addc_co_u32_e32 v73, vcc, 0, v71, vcc
	s_barrier
	global_load_dwordx4 v[102:105], v[70:71], off nt
	global_load_dwordx4 v[98:101], v[72:73], off nt
	v_add_co_u32_e32 v72, vcc, 0x20000, v70
	s_lshl_b32 s10, s82, 5
	s_nop 0
	v_addc_co_u32_e32 v73, vcc, 0, v71, vcc
	v_add_co_u32_e32 v74, vcc, 0x22000, v70
	s_and_b32 s10, s10, 0x7fffff80
	s_nop 0
	v_addc_co_u32_e32 v75, vcc, 0, v71, vcc
	global_load_dwordx4 v[106:109], v[72:73], off nt
	global_load_dwordx4 v[94:97], v[74:75], off nt
	v_add_co_u32_e32 v72, vcc, 0x40000, v70
	v_add_u32_e32 v147, s10, v148
	s_nop 0
	v_addc_co_u32_e32 v73, vcc, 0, v71, vcc
	v_add_co_u32_e32 v74, vcc, 0x42000, v70
	s_lshl_b32 s10, s82, 4
	s_nop 0
	v_addc_co_u32_e32 v75, vcc, 0, v71, vcc
	global_load_dwordx4 v[110:113], v[72:73], off nt
	global_load_dwordx4 v[90:93], v[74:75], off nt
	v_add_co_u32_e32 v72, vcc, 0x60000, v70
	v_and_or_b32 v160, s10, 48, v147
	s_nop 0
	v_addc_co_u32_e32 v73, vcc, 0, v71, vcc
	v_add_co_u32_e32 v74, vcc, 0x62000, v70
	v_ashrrev_i32_e32 v161, 31, v160
	s_nop 0
	v_addc_co_u32_e32 v75, vcc, 0, v71, vcc
	global_load_dwordx4 v[114:117], v[72:73], off nt
	global_load_dwordx4 v[86:89], v[74:75], off nt
	v_add_co_u32_e32 v72, vcc, 0x80000, v70
	v_ashrrev_i32_e32 v147, 31, v146
	s_nop 0
	v_addc_co_u32_e32 v73, vcc, 0, v71, vcc
	v_add_co_u32_e32 v74, vcc, 0x82000, v70
	s_mov_b64 s[36:37], 0
	s_nop 0
	v_addc_co_u32_e32 v75, vcc, 0, v71, vcc
	global_load_dwordx4 v[118:121], v[72:73], off nt
	global_load_dwordx4 v[82:85], v[74:75], off nt
	v_add_co_u32_e32 v72, vcc, 0xa0000, v70
	s_waitcnt vmcnt(9)
	v_lshlrev_b32_e32 v162, 16, v102
	v_addc_co_u32_e32 v73, vcc, 0, v71, vcc
	v_add_co_u32_e32 v74, vcc, 0xa2000, v70
	v_and_b32_e32 v163, 0xffff0000, v102
	s_nop 0
	v_addc_co_u32_e32 v75, vcc, 0, v71, vcc
	global_load_dwordx4 v[122:125], v[72:73], off nt
	global_load_dwordx4 v[78:81], v[74:75], off nt
	v_add_co_u32_e32 v72, vcc, 0xc0000, v70
	v_lshlrev_b32_e32 v102, 16, v103
	s_nop 0
	v_addc_co_u32_e32 v73, vcc, 0, v71, vcc
	v_add_co_u32_e32 v74, vcc, 0xc2000, v70
	v_and_b32_e32 v103, 0xffff0000, v103
	s_nop 0
	v_addc_co_u32_e32 v75, vcc, 0, v71, vcc
	global_load_dwordx4 v[126:129], v[72:73], off nt
	s_nop 0
	global_load_dwordx4 v[74:77], v[74:75], off nt
	v_add_co_u32_e32 v72, vcc, 0xe0000, v70
	v_pk_add_f32 v[162:163], v[162:163], 0 op_sel_hi:[1,0]
	s_nop 0
	v_addc_co_u32_e32 v73, vcc, 0, v71, vcc
	v_add_co_u32_e32 v70, vcc, 0xe2000, v70
	v_pk_add_f32 v[102:103], v[102:103], 0 op_sel_hi:[1,0]
	s_nop 0
	v_addc_co_u32_e32 v71, vcc, 0, v71, vcc
	global_load_dwordx4 v[156:159], v[72:73], off nt
	s_nop 0
	global_load_dwordx4 v[70:73], v[70:71], off nt
	v_lshlrev_b32_e32 v164, 16, v104
	v_and_b32_e32 v165, 0xffff0000, v104
	v_lshlrev_b32_e32 v104, 16, v105
	v_and_b32_e32 v105, 0xffff0000, v105
	s_waitcnt vmcnt(13)
	v_lshlrev_b32_e32 v166, 16, v106
	v_and_b32_e32 v167, 0xffff0000, v106
	v_lshlrev_b32_e32 v106, 16, v107
	v_and_b32_e32 v107, 0xffff0000, v107
	v_pk_add_f32 v[164:165], v[164:165], 0 op_sel_hi:[1,0]
	v_pk_add_f32 v[104:105], v[104:105], 0 op_sel_hi:[1,0]
	v_pk_add_f32 v[102:103], v[102:103], v[106:107]
	v_pk_add_f32 v[106:107], v[162:163], v[166:167]
	v_lshlrev_b32_e32 v162, 16, v108
	v_and_b32_e32 v163, 0xffff0000, v108
	v_lshlrev_b32_e32 v108, 16, v109
	v_and_b32_e32 v109, 0xffff0000, v109
	v_pk_add_f32 v[104:105], v[104:105], v[108:109]
	v_pk_add_f32 v[108:109], v[164:165], v[162:163]
	s_waitcnt vmcnt(11)
	v_lshlrev_b32_e32 v162, 16, v110
	v_and_b32_e32 v163, 0xffff0000, v110
	v_lshlrev_b32_e32 v110, 16, v111
	v_and_b32_e32 v111, 0xffff0000, v111
	v_pk_add_f32 v[102:103], v[102:103], v[110:111]
	v_lshlrev_b32_e32 v110, 16, v112
	v_and_b32_e32 v111, 0xffff0000, v112
	v_lshlrev_b32_e32 v112, 16, v113
	v_and_b32_e32 v113, 0xffff0000, v113
	v_pk_add_f32 v[106:107], v[106:107], v[162:163]
	v_pk_add_f32 v[108:109], v[108:109], v[110:111]
	v_pk_add_f32 v[104:105], v[104:105], v[112:113]
	s_waitcnt vmcnt(9)
	v_lshlrev_b32_e32 v110, 16, v114
	v_and_b32_e32 v111, 0xffff0000, v114
	v_lshlrev_b32_e32 v112, 16, v115
	v_and_b32_e32 v113, 0xffff0000, v115
	v_pk_add_f32 v[102:103], v[102:103], v[112:113]
	v_pk_add_f32 v[106:107], v[106:107], v[110:111]
	v_lshlrev_b32_e32 v110, 16, v116
	v_and_b32_e32 v111, 0xffff0000, v116
	v_lshlrev_b32_e32 v112, 16, v117
	v_and_b32_e32 v113, 0xffff0000, v117
	v_pk_add_f32 v[104:105], v[104:105], v[112:113]
	v_pk_add_f32 v[108:109], v[108:109], v[110:111]
	s_waitcnt vmcnt(7)
	v_lshlrev_b32_e32 v110, 16, v118
	v_and_b32_e32 v111, 0xffff0000, v118
	v_lshlrev_b32_e32 v112, 16, v119
	v_and_b32_e32 v113, 0xffff0000, v119
	v_pk_add_f32 v[106:107], v[106:107], v[110:111]
	v_pk_add_f32 v[102:103], v[102:103], v[112:113]
	v_lshlrev_b32_e32 v110, 16, v120
	v_and_b32_e32 v111, 0xffff0000, v120
	v_lshlrev_b32_e32 v112, 16, v121
	v_and_b32_e32 v113, 0xffff0000, v121
	v_pk_add_f32 v[108:109], v[108:109], v[110:111]
	v_pk_add_f32 v[104:105], v[104:105], v[112:113]
	s_waitcnt vmcnt(5)
	v_lshlrev_b32_e32 v110, 16, v122
	v_and_b32_e32 v111, 0xffff0000, v122
	v_lshlrev_b32_e32 v112, 16, v123
	v_and_b32_e32 v113, 0xffff0000, v123
	v_pk_add_f32 v[102:103], v[102:103], v[112:113]
	v_pk_add_f32 v[106:107], v[106:107], v[110:111]
	v_lshlrev_b32_e32 v110, 16, v124
	v_and_b32_e32 v111, 0xffff0000, v124
	v_lshlrev_b32_e32 v112, 16, v125
	v_and_b32_e32 v113, 0xffff0000, v125
	v_pk_add_f32 v[104:105], v[104:105], v[112:113]
	v_pk_add_f32 v[108:109], v[108:109], v[110:111]
	s_waitcnt vmcnt(3)
	v_lshlrev_b32_e32 v110, 16, v126
	v_and_b32_e32 v111, 0xffff0000, v126
	v_lshlrev_b32_e32 v112, 16, v127
	v_and_b32_e32 v113, 0xffff0000, v127
	v_pk_add_f32 v[106:107], v[106:107], v[110:111]
	v_pk_add_f32 v[102:103], v[102:103], v[112:113]
	v_lshlrev_b32_e32 v110, 16, v128
	v_and_b32_e32 v111, 0xffff0000, v128
	v_lshlrev_b32_e32 v112, 16, v129
	v_and_b32_e32 v113, 0xffff0000, v129
	v_pk_add_f32 v[108:109], v[108:109], v[110:111]
	v_pk_add_f32 v[104:105], v[104:105], v[112:113]
	s_waitcnt vmcnt(1)
	v_lshlrev_b32_e32 v110, 16, v156
	v_and_b32_e32 v111, 0xffff0000, v156
	v_lshlrev_b32_e32 v112, 16, v157
	v_and_b32_e32 v113, 0xffff0000, v157
	v_pk_add_f32 v[102:103], v[102:103], v[112:113]
	v_pk_add_f32 v[106:107], v[106:107], v[110:111]
	v_lshlrev_b32_e32 v110, 16, v158
	v_and_b32_e32 v111, 0xffff0000, v158
	v_lshlrev_b32_e32 v112, 16, v159
	v_and_b32_e32 v113, 0xffff0000, v159
	v_pk_add_f32 v[112:113], v[104:105], v[112:113]
	v_pk_add_f32 v[108:109], v[108:109], v[110:111]
	v_cvt_pk_bf16_f32 v105, v102, v103
	v_lshlrev_b64 v[102:103], 12, v[160:161]
	v_cvt_pk_bf16_f32 v104, v106, v107
	v_cvt_pk_bf16_f32 v106, v108, v109
	v_lshl_add_u64 v[108:109], s[40:41], 0, v[102:103]
	v_cvt_pk_bf16_f32 v107, v112, v113
	v_lshl_add_u64 v[108:109], v[146:147], 1, v[108:109]
	global_store_dwordx4 v[108:109], v[104:107], off
	v_lshlrev_b32_e32 v108, 16, v94
	v_and_b32_e32 v109, 0xffff0000, v94
	v_lshlrev_b32_e32 v104, 16, v98
	v_and_b32_e32 v105, 0xffff0000, v98
	v_lshlrev_b32_e32 v98, 16, v99
	v_and_b32_e32 v99, 0xffff0000, v99
	v_pk_add_f32 v[104:105], v[104:105], 0 op_sel_hi:[1,0]
	v_pk_add_f32 v[98:99], v[98:99], 0 op_sel_hi:[1,0]
	v_lshlrev_b32_e32 v106, 16, v100
	v_and_b32_e32 v107, 0xffff0000, v100
	v_lshlrev_b32_e32 v100, 16, v101
	v_and_b32_e32 v101, 0xffff0000, v101
	v_lshlrev_b32_e32 v94, 16, v95
	v_and_b32_e32 v95, 0xffff0000, v95
	v_pk_add_f32 v[106:107], v[106:107], 0 op_sel_hi:[1,0]
	v_pk_add_f32 v[100:101], v[100:101], 0 op_sel_hi:[1,0]
	v_pk_add_f32 v[94:95], v[98:99], v[94:95]
	v_pk_add_f32 v[98:99], v[104:105], v[108:109]
	v_lshlrev_b32_e32 v104, 16, v96
	v_and_b32_e32 v105, 0xffff0000, v96
	v_lshlrev_b32_e32 v96, 16, v97
	v_and_b32_e32 v97, 0xffff0000, v97
	v_pk_add_f32 v[96:97], v[100:101], v[96:97]
	v_pk_add_f32 v[100:101], v[106:107], v[104:105]
	v_lshlrev_b32_e32 v104, 16, v90
	v_and_b32_e32 v105, 0xffff0000, v90
	v_lshlrev_b32_e32 v90, 16, v91
	v_and_b32_e32 v91, 0xffff0000, v91
	v_pk_add_f32 v[90:91], v[94:95], v[90:91]
	v_lshlrev_b32_e32 v94, 16, v92
	v_and_b32_e32 v95, 0xffff0000, v92
	v_lshlrev_b32_e32 v92, 16, v93
	v_and_b32_e32 v93, 0xffff0000, v93
	v_pk_add_f32 v[98:99], v[98:99], v[104:105]
	v_pk_add_f32 v[92:93], v[96:97], v[92:93]
	v_lshlrev_b32_e32 v96, 16, v86
	v_and_b32_e32 v97, 0xffff0000, v86
	v_lshlrev_b32_e32 v86, 16, v87
	v_and_b32_e32 v87, 0xffff0000, v87
	v_pk_add_f32 v[94:95], v[100:101], v[94:95]
	v_pk_add_f32 v[86:87], v[90:91], v[86:87]
	v_pk_add_f32 v[90:91], v[98:99], v[96:97]
	v_lshlrev_b32_e32 v96, 16, v88
	v_and_b32_e32 v97, 0xffff0000, v88
	v_lshlrev_b32_e32 v88, 16, v89
	v_and_b32_e32 v89, 0xffff0000, v89
	v_pk_add_f32 v[88:89], v[92:93], v[88:89]
	v_pk_add_f32 v[92:93], v[94:95], v[96:97]
	v_lshlrev_b32_e32 v94, 16, v82
	v_and_b32_e32 v95, 0xffff0000, v82
	v_lshlrev_b32_e32 v82, 16, v83
	v_and_b32_e32 v83, 0xffff0000, v83
	v_pk_add_f32 v[82:83], v[86:87], v[82:83]
	v_lshlrev_b32_e32 v86, 16, v84
	v_and_b32_e32 v87, 0xffff0000, v84
	v_lshlrev_b32_e32 v84, 16, v85
	v_and_b32_e32 v85, 0xffff0000, v85
	v_pk_add_f32 v[90:91], v[90:91], v[94:95]
	v_pk_add_f32 v[84:85], v[88:89], v[84:85]
	v_lshlrev_b32_e32 v88, 16, v78
	v_and_b32_e32 v89, 0xffff0000, v78
	v_lshlrev_b32_e32 v78, 16, v79
	v_and_b32_e32 v79, 0xffff0000, v79
	v_pk_add_f32 v[86:87], v[92:93], v[86:87]
	v_pk_add_f32 v[78:79], v[82:83], v[78:79]
	v_pk_add_f32 v[82:83], v[90:91], v[88:89]
	v_lshlrev_b32_e32 v88, 16, v80
	v_and_b32_e32 v89, 0xffff0000, v80
	v_lshlrev_b32_e32 v80, 16, v81
	v_and_b32_e32 v81, 0xffff0000, v81
	v_pk_add_f32 v[80:81], v[84:85], v[80:81]
	v_pk_add_f32 v[84:85], v[86:87], v[88:89]
	v_lshlrev_b32_e32 v86, 16, v74
	v_and_b32_e32 v87, 0xffff0000, v74
	v_lshlrev_b32_e32 v74, 16, v75
	v_and_b32_e32 v75, 0xffff0000, v75
	v_pk_add_f32 v[74:75], v[78:79], v[74:75]
	v_lshlrev_b32_e32 v78, 16, v76
	v_and_b32_e32 v79, 0xffff0000, v76
	v_lshlrev_b32_e32 v76, 16, v77
	v_and_b32_e32 v77, 0xffff0000, v77
	v_pk_add_f32 v[78:79], v[84:85], v[78:79]
	s_waitcnt vmcnt(1)
	v_lshlrev_b32_e32 v84, 16, v70
	v_and_b32_e32 v85, 0xffff0000, v70
	v_lshlrev_b32_e32 v70, 16, v71
	v_and_b32_e32 v71, 0xffff0000, v71
	v_pk_add_f32 v[82:83], v[82:83], v[86:87]
	v_pk_add_f32 v[80:81], v[80:81], v[76:77]
	v_pk_add_f32 v[76:77], v[74:75], v[70:71]
	v_lshlrev_b32_e32 v70, 16, v72
	v_and_b32_e32 v71, 0xffff0000, v72
	v_lshlrev_b32_e32 v72, 16, v73
	v_and_b32_e32 v73, 0xffff0000, v73
	v_pk_add_f32 v[74:75], v[82:83], v[84:85]
	v_pk_add_f32 v[72:73], v[80:81], v[72:73]
	v_pk_add_f32 v[70:71], v[78:79], v[70:71]

.LBB0_705:
	v_lshl_add_u32 v148, s8, 8, v1
	v_lshl_or_b32 v146, s46, 8, v151
	s_mov_b64 s[30:31], -1
	s_cmp_gt_i32 s77, -1
	v_cvt_pk_bf16_f32 v66, v66, v67
	v_cvt_pk_bf16_f32 v67, v68, v69
	v_cvt_pk_bf16_f32 v68, v126, v127
	v_cvt_pk_bf16_f32 v69, v128, v129
	v_cvt_pk_bf16_f32 v62, v62, v63
	v_cvt_pk_bf16_f32 v63, v64, v65
	v_cvt_pk_bf16_f32 v64, v58, v59
	v_cvt_pk_bf16_f32 v65, v60, v61
	v_cvt_pk_bf16_f32 v58, v122, v123
	v_cvt_pk_bf16_f32 v59, v124, v125
	v_cvt_pk_bf16_f32 v60, v118, v119
	v_cvt_pk_bf16_f32 v61, v120, v121
	v_cvt_pk_bf16_f32 v54, v54, v55
	v_cvt_pk_bf16_f32 v55, v56, v57
	v_cvt_pk_bf16_f32 v56, v50, v51
	v_cvt_pk_bf16_f32 v57, v52, v53
	v_cvt_pk_bf16_f32 v50, v114, v115
	v_cvt_pk_bf16_f32 v51, v116, v117
	v_cvt_pk_bf16_f32 v52, v110, v111
	v_cvt_pk_bf16_f32 v53, v112, v113
	v_cvt_pk_bf16_f32 v46, v46, v47
	v_cvt_pk_bf16_f32 v47, v48, v49
	v_cvt_pk_bf16_f32 v48, v42, v43
	v_cvt_pk_bf16_f32 v49, v44, v45
	v_cvt_pk_bf16_f32 v42, v106, v107
	v_cvt_pk_bf16_f32 v43, v108, v109
	v_cvt_pk_bf16_f32 v44, v102, v103
	v_cvt_pk_bf16_f32 v45, v104, v105
	v_cvt_pk_bf16_f32 v38, v38, v39
	v_cvt_pk_bf16_f32 v39, v40, v41
	v_cvt_pk_bf16_f32 v40, v98, v99
	v_cvt_pk_bf16_f32 v41, v100, v101
	v_cvt_pk_bf16_f32 v34, v34, v35
	v_cvt_pk_bf16_f32 v35, v36, v37
	v_cvt_pk_bf16_f32 v36, v94, v95
	v_cvt_pk_bf16_f32 v37, v96, v97
	v_cvt_pk_bf16_f32 v30, v30, v31
	v_cvt_pk_bf16_f32 v31, v32, v33
	v_cvt_pk_bf16_f32 v32, v26, v27
	v_cvt_pk_bf16_f32 v33, v28, v29
	v_cvt_pk_bf16_f32 v26, v90, v91
	v_cvt_pk_bf16_f32 v27, v92, v93
	v_cvt_pk_bf16_f32 v28, v86, v87
	v_cvt_pk_bf16_f32 v29, v88, v89
	v_cvt_pk_bf16_f32 v22, v22, v23
	v_cvt_pk_bf16_f32 v23, v24, v25
	v_cvt_pk_bf16_f32 v24, v18, v19
	v_cvt_pk_bf16_f32 v25, v20, v21
	v_cvt_pk_bf16_f32 v18, v82, v83
	v_cvt_pk_bf16_f32 v19, v84, v85
	v_cvt_pk_bf16_f32 v20, v78, v79
	v_cvt_pk_bf16_f32 v21, v80, v81
	v_cvt_pk_bf16_f32 v14, v14, v15
	v_cvt_pk_bf16_f32 v15, v16, v17
	v_cvt_pk_bf16_f32 v16, v10, v11
	v_cvt_pk_bf16_f32 v17, v12, v13
	v_cvt_pk_bf16_f32 v10, v74, v75
	v_cvt_pk_bf16_f32 v11, v76, v77
	v_cvt_pk_bf16_f32 v12, v70, v71
	v_cvt_pk_bf16_f32 v13, v72, v73
	s_cbranch_scc0 .LBB0_719
	s_lshl_b32 s30, s52, 3
	s_add_i32 s34, s30, s77
	s_ashr_i32 s35, s34, 31
	s_lshl_b64 s[34:35], s[34:35], 17
	v_lshl_add_u64 v[74:75], v[138:139], 0, s[34:35]
	s_movk_i32 s8, 0x2000
	v_add_co_u32_e32 v70, vcc, s8, v74
	s_movk_i32 s8, 0x4000
	s_nop 0
	v_addc_co_u32_e32 v71, vcc, 0, v75, vcc
	global_store_dwordx4 v[70:71], v[62:65], off nt
	v_add_co_u32_e32 v70, vcc, s8, v74
	s_movk_i32 s8, 0x6000
	s_nop 0
	v_addc_co_u32_e32 v71, vcc, 0, v75, vcc
	global_store_dwordx4 v[70:71], v[58:61], off nt
	v_add_co_u32_e32 v70, vcc, s8, v74
	s_mov_b32 s8, 0x8000
	s_nop 0
	v_addc_co_u32_e32 v71, vcc, 0, v75, vcc
	global_store_dwordx4 v[70:71], v[54:57], off nt
	v_add_co_u32_e32 v70, vcc, s8, v74
	s_mov_b32 s8, 0xa000
	s_nop 0
	v_addc_co_u32_e32 v71, vcc, 0, v75, vcc
	global_store_dwordx4 v[70:71], v[50:53], off nt
	v_add_co_u32_e32 v70, vcc, s8, v74
	s_mov_b32 s8, 0xc000
	s_nop 0
	v_addc_co_u32_e32 v71, vcc, 0, v75, vcc
	global_store_dwordx4 v[70:71], v[46:49], off nt
	v_add_co_u32_e32 v70, vcc, s8, v74
	s_mov_b32 s8, 0xe000
	s_nop 0
	v_addc_co_u32_e32 v71, vcc, 0, v75, vcc
	global_store_dwordx4 v[70:71], v[42:45], off nt
	v_add_co_u32_e32 v70, vcc, s8, v74
	s_mov_b32 s8, 0x10000
	s_nop 0
	v_addc_co_u32_e32 v71, vcc, 0, v75, vcc
	global_store_dwordx4 v[70:71], v[38:41], off nt
	v_add_co_u32_e32 v70, vcc, s8, v74
	s_mov_b32 s8, 0x12000
	s_nop 0
	v_addc_co_u32_e32 v71, vcc, 0, v75, vcc
	global_store_dwordx4 v[70:71], v[34:37], off nt
	v_add_co_u32_e32 v70, vcc, s8, v74
	s_mov_b32 s8, 0x14000
	s_nop 0
	v_addc_co_u32_e32 v71, vcc, 0, v75, vcc
	global_store_dwordx4 v[70:71], v[30:33], off nt
	v_add_co_u32_e32 v70, vcc, s8, v74
	s_mov_b32 s8, 0x16000
	s_nop 0
	v_addc_co_u32_e32 v71, vcc, 0, v75, vcc
	global_store_dwordx4 v[70:71], v[26:29], off nt
	v_add_co_u32_e32 v70, vcc, s8, v74
	s_mov_b32 s8, 0x18000
	s_nop 0
	v_addc_co_u32_e32 v71, vcc, 0, v75, vcc
	global_store_dwordx4 v[70:71], v[22:25], off nt
	v_add_co_u32_e32 v70, vcc, s8, v74
	s_mov_b32 s8, 0x1a000
	s_nop 0
	v_addc_co_u32_e32 v71, vcc, 0, v75, vcc
	global_store_dwordx4 v[70:71], v[18:21], off nt
	v_add_co_u32_e32 v70, vcc, s8, v74
	s_mov_b32 s8, 0x1c000
	s_nop 0
	v_addc_co_u32_e32 v71, vcc, 0, v75, vcc
	global_store_dwordx4 v[70:71], v[14:17], off nt
	v_add_co_u32_e32 v70, vcc, s8, v74
	global_store_dwordx4 v[74:75], v[66:69], off nt
	s_nop 0
	v_addc_co_u32_e32 v71, vcc, 0, v75, vcc
	v_add_co_u32_e32 v74, vcc, 0x1e000, v74
	global_store_dwordx4 v[70:71], v[10:13], off nt
	v_cvt_pk_bf16_f32 v70, v6, v7
	v_cvt_pk_bf16_f32 v71, v8, v9
	v_cvt_pk_bf16_f32 v72, v2, v3
	v_cvt_pk_bf16_f32 v73, v4, v5
	v_addc_co_u32_e32 v75, vcc, 0, v75, vcc
	global_store_dwordx4 v[74:75], v[70:73], off nt
	s_waitcnt vmcnt(0)
	s_waitcnt vmcnt(0)
	s_barrier
	s_and_saveexec_b64 s[34:35], s[0:1]
	s_cbranch_execz .LBB0_718
	s_lshl_b32 s36, s52, 6
	s_mov_b64 s[46:47], exec
	s_ashr_i32 s37, s36, 31
	s_lshl_b64 s[36:37], s[36:37], 2
	buffer_wbl2 sc1
	s_waitcnt vmcnt(0)
	v_mbcnt_lo_u32_b32 v70, s46, 0
	s_add_u32 s36, s56, s36
	v_mbcnt_hi_u32_b32 v70, s47, v70
	s_addc_u32 s37, s57, s37
	v_cmp_eq_u32_e32 vcc, 0, v70
	s_and_saveexec_b64 s[52:53], vcc
	s_cbranch_execz .LBB0_709
	s_bcnt1_i32_b64 s8, s[46:47]
	v_mov_b32_e32 v70, s8
	global_atomic_add v133, v70, s[36:37]

.LBB0_718:
	s_or_b64 exec, exec, s[34:35]
	s_ashr_i32 s31, s30, 31
	s_lshl_b64 s[30:31], s[30:31], 17
	s_lshl_b32 s8, s77, 1
	v_lshl_add_u64 v[70:71], v[138:139], 0, s[30:31]
	s_lshl_b64 s[30:31], s[8:9], 13
	v_lshl_add_u64 v[70:71], v[70:71], 0, s[30:31]
	v_add_co_u32_e32 v72, vcc, 0x2000, v70
	s_nop 1
	v_addc_co_u32_e32 v73, vcc, 0, v71, vcc
	s_barrier
	global_load_dwordx4 v[102:105], v[70:71], off nt
	global_load_dwordx4 v[98:101], v[72:73], off nt
	v_add_co_u32_e32 v72, vcc, 0x20000, v70
	s_lshl_b32 s8, s77, 5
	s_nop 0
	v_addc_co_u32_e32 v73, vcc, 0, v71, vcc
	v_add_co_u32_e32 v74, vcc, 0x22000, v70
	s_and_b32 s8, s8, 0x7fffff80
	s_nop 0
	v_addc_co_u32_e32 v75, vcc, 0, v71, vcc
	global_load_dwordx4 v[106:109], v[72:73], off nt
	global_load_dwordx4 v[94:97], v[74:75], off nt
	v_add_co_u32_e32 v72, vcc, 0x40000, v70
	v_add_u32_e32 v147, s8, v148
	s_nop 0
	v_addc_co_u32_e32 v73, vcc, 0, v71, vcc
	v_add_co_u32_e32 v74, vcc, 0x42000, v70
	s_lshl_b32 s8, s77, 4
	s_nop 0
	v_addc_co_u32_e32 v75, vcc, 0, v71, vcc
	global_load_dwordx4 v[110:113], v[72:73], off nt
	global_load_dwordx4 v[90:93], v[74:75], off nt
	v_add_co_u32_e32 v72, vcc, 0x60000, v70
	v_and_or_b32 v160, s8, 48, v147
	s_nop 0
	v_addc_co_u32_e32 v73, vcc, 0, v71, vcc
	v_add_co_u32_e32 v74, vcc, 0x62000, v70
	v_ashrrev_i32_e32 v161, 31, v160
	s_nop 0
	v_addc_co_u32_e32 v75, vcc, 0, v71, vcc
	global_load_dwordx4 v[114:117], v[72:73], off nt
	global_load_dwordx4 v[86:89], v[74:75], off nt
	v_add_co_u32_e32 v72, vcc, 0x80000, v70
	v_ashrrev_i32_e32 v147, 31, v146
	s_nop 0
	v_addc_co_u32_e32 v73, vcc, 0, v71, vcc
	v_add_co_u32_e32 v74, vcc, 0x82000, v70
	s_mov_b64 s[30:31], 0
	s_nop 0
	v_addc_co_u32_e32 v75, vcc, 0, v71, vcc
	global_load_dwordx4 v[118:121], v[72:73], off nt
	global_load_dwordx4 v[82:85], v[74:75], off nt
	v_add_co_u32_e32 v72, vcc, 0xa0000, v70
	s_waitcnt vmcnt(9)
	v_lshlrev_b32_e32 v162, 16, v102
	v_addc_co_u32_e32 v73, vcc, 0, v71, vcc
	v_add_co_u32_e32 v74, vcc, 0xa2000, v70
	v_and_b32_e32 v163, 0xffff0000, v102
	s_nop 0
	v_addc_co_u32_e32 v75, vcc, 0, v71, vcc
	global_load_dwordx4 v[122:125], v[72:73], off nt
	global_load_dwordx4 v[78:81], v[74:75], off nt
	v_add_co_u32_e32 v72, vcc, 0xc0000, v70
	v_lshlrev_b32_e32 v102, 16, v103
	s_nop 0
	v_addc_co_u32_e32 v73, vcc, 0, v71, vcc
	v_add_co_u32_e32 v74, vcc, 0xc2000, v70
	v_and_b32_e32 v103, 0xffff0000, v103
	s_nop 0
	v_addc_co_u32_e32 v75, vcc, 0, v71, vcc
	global_load_dwordx4 v[126:129], v[72:73], off nt
	s_nop 0
	global_load_dwordx4 v[74:77], v[74:75], off nt
	v_add_co_u32_e32 v72, vcc, 0xe0000, v70
	v_pk_add_f32 v[162:163], v[162:163], 0 op_sel_hi:[1,0]
	s_nop 0
	v_addc_co_u32_e32 v73, vcc, 0, v71, vcc
	v_add_co_u32_e32 v70, vcc, 0xe2000, v70
	v_pk_add_f32 v[102:103], v[102:103], 0 op_sel_hi:[1,0]
	s_nop 0
	v_addc_co_u32_e32 v71, vcc, 0, v71, vcc
	global_load_dwordx4 v[156:159], v[72:73], off nt
	s_nop 0
	global_load_dwordx4 v[70:73], v[70:71], off nt
	v_lshlrev_b32_e32 v164, 16, v104
	v_and_b32_e32 v165, 0xffff0000, v104
	v_lshlrev_b32_e32 v104, 16, v105
	v_and_b32_e32 v105, 0xffff0000, v105
	s_waitcnt vmcnt(13)
	v_lshlrev_b32_e32 v166, 16, v106
	v_and_b32_e32 v167, 0xffff0000, v106
	v_lshlrev_b32_e32 v106, 16, v107
	v_and_b32_e32 v107, 0xffff0000, v107
	v_pk_add_f32 v[164:165], v[164:165], 0 op_sel_hi:[1,0]
	v_pk_add_f32 v[104:105], v[104:105], 0 op_sel_hi:[1,0]
	v_pk_add_f32 v[102:103], v[102:103], v[106:107]
	v_pk_add_f32 v[106:107], v[162:163], v[166:167]
	v_lshlrev_b32_e32 v162, 16, v108
	v_and_b32_e32 v163, 0xffff0000, v108
	v_lshlrev_b32_e32 v108, 16, v109
	v_and_b32_e32 v109, 0xffff0000, v109
	v_pk_add_f32 v[104:105], v[104:105], v[108:109]
	v_pk_add_f32 v[108:109], v[164:165], v[162:163]
	s_waitcnt vmcnt(11)
	v_lshlrev_b32_e32 v162, 16, v110
	v_and_b32_e32 v163, 0xffff0000, v110
	v_lshlrev_b32_e32 v110, 16, v111
	v_and_b32_e32 v111, 0xffff0000, v111
	v_pk_add_f32 v[102:103], v[102:103], v[110:111]
	v_lshlrev_b32_e32 v110, 16, v112
	v_and_b32_e32 v111, 0xffff0000, v112
	v_lshlrev_b32_e32 v112, 16, v113
	v_and_b32_e32 v113, 0xffff0000, v113
	v_pk_add_f32 v[106:107], v[106:107], v[162:163]
	v_pk_add_f32 v[108:109], v[108:109], v[110:111]
	v_pk_add_f32 v[104:105], v[104:105], v[112:113]
	s_waitcnt vmcnt(9)
	v_lshlrev_b32_e32 v110, 16, v114
	v_and_b32_e32 v111, 0xffff0000, v114
	v_lshlrev_b32_e32 v112, 16, v115
	v_and_b32_e32 v113, 0xffff0000, v115
	v_pk_add_f32 v[102:103], v[102:103], v[112:113]
	v_pk_add_f32 v[106:107], v[106:107], v[110:111]
	v_lshlrev_b32_e32 v110, 16, v116
	v_and_b32_e32 v111, 0xffff0000, v116
	v_lshlrev_b32_e32 v112, 16, v117
	v_and_b32_e32 v113, 0xffff0000, v117
	v_pk_add_f32 v[104:105], v[104:105], v[112:113]
	v_pk_add_f32 v[108:109], v[108:109], v[110:111]
	s_waitcnt vmcnt(7)
	v_lshlrev_b32_e32 v110, 16, v118
	v_and_b32_e32 v111, 0xffff0000, v118
	v_lshlrev_b32_e32 v112, 16, v119
	v_and_b32_e32 v113, 0xffff0000, v119
	v_pk_add_f32 v[106:107], v[106:107], v[110:111]
	v_pk_add_f32 v[102:103], v[102:103], v[112:113]
	v_lshlrev_b32_e32 v110, 16, v120
	v_and_b32_e32 v111, 0xffff0000, v120
	v_lshlrev_b32_e32 v112, 16, v121
	v_and_b32_e32 v113, 0xffff0000, v121
	v_pk_add_f32 v[108:109], v[108:109], v[110:111]
	v_pk_add_f32 v[104:105], v[104:105], v[112:113]
	s_waitcnt vmcnt(5)
	v_lshlrev_b32_e32 v110, 16, v122
	v_and_b32_e32 v111, 0xffff0000, v122
	v_lshlrev_b32_e32 v112, 16, v123
	v_and_b32_e32 v113, 0xffff0000, v123
	v_pk_add_f32 v[102:103], v[102:103], v[112:113]
	v_pk_add_f32 v[106:107], v[106:107], v[110:111]
	v_lshlrev_b32_e32 v110, 16, v124
	v_and_b32_e32 v111, 0xffff0000, v124
	v_lshlrev_b32_e32 v112, 16, v125
	v_and_b32_e32 v113, 0xffff0000, v125
	v_pk_add_f32 v[104:105], v[104:105], v[112:113]
	v_pk_add_f32 v[108:109], v[108:109], v[110:111]
	s_waitcnt vmcnt(3)
	v_lshlrev_b32_e32 v110, 16, v126
	v_and_b32_e32 v111, 0xffff0000, v126
	v_lshlrev_b32_e32 v112, 16, v127
	v_and_b32_e32 v113, 0xffff0000, v127
	v_pk_add_f32 v[106:107], v[106:107], v[110:111]
	v_pk_add_f32 v[102:103], v[102:103], v[112:113]
	v_lshlrev_b32_e32 v110, 16, v128
	v_and_b32_e32 v111, 0xffff0000, v128
	v_lshlrev_b32_e32 v112, 16, v129
	v_and_b32_e32 v113, 0xffff0000, v129
	v_pk_add_f32 v[108:109], v[108:109], v[110:111]
	v_pk_add_f32 v[104:105], v[104:105], v[112:113]
	s_waitcnt vmcnt(1)
	v_lshlrev_b32_e32 v110, 16, v156
	v_and_b32_e32 v111, 0xffff0000, v156
	v_lshlrev_b32_e32 v112, 16, v157
	v_and_b32_e32 v113, 0xffff0000, v157
	v_pk_add_f32 v[102:103], v[102:103], v[112:113]
	v_pk_add_f32 v[106:107], v[106:107], v[110:111]
	v_lshlrev_b32_e32 v110, 16, v158
	v_and_b32_e32 v111, 0xffff0000, v158
	v_lshlrev_b32_e32 v112, 16, v159
	v_and_b32_e32 v113, 0xffff0000, v159
	v_pk_add_f32 v[112:113], v[104:105], v[112:113]
	v_pk_add_f32 v[108:109], v[108:109], v[110:111]
	v_cvt_pk_bf16_f32 v105, v102, v103
	v_lshlrev_b64 v[102:103], 12, v[160:161]
	v_cvt_pk_bf16_f32 v104, v106, v107
	v_cvt_pk_bf16_f32 v106, v108, v109
	v_lshl_add_u64 v[108:109], s[40:41], 0, v[102:103]
	v_cvt_pk_bf16_f32 v107, v112, v113
	v_lshl_add_u64 v[108:109], v[146:147], 1, v[108:109]
	global_store_dwordx4 v[108:109], v[104:107], off
	v_lshlrev_b32_e32 v108, 16, v94
	v_and_b32_e32 v109, 0xffff0000, v94
	v_lshlrev_b32_e32 v104, 16, v98
	v_and_b32_e32 v105, 0xffff0000, v98
	v_lshlrev_b32_e32 v98, 16, v99
	v_and_b32_e32 v99, 0xffff0000, v99
	v_pk_add_f32 v[104:105], v[104:105], 0 op_sel_hi:[1,0]
	v_pk_add_f32 v[98:99], v[98:99], 0 op_sel_hi:[1,0]
	v_lshlrev_b32_e32 v106, 16, v100
	v_and_b32_e32 v107, 0xffff0000, v100
	v_lshlrev_b32_e32 v100, 16, v101
	v_and_b32_e32 v101, 0xffff0000, v101
	v_lshlrev_b32_e32 v94, 16, v95
	v_and_b32_e32 v95, 0xffff0000, v95
	v_pk_add_f32 v[106:107], v[106:107], 0 op_sel_hi:[1,0]
	v_pk_add_f32 v[100:101], v[100:101], 0 op_sel_hi:[1,0]
	v_pk_add_f32 v[94:95], v[98:99], v[94:95]
	v_pk_add_f32 v[98:99], v[104:105], v[108:109]
	v_lshlrev_b32_e32 v104, 16, v96
	v_and_b32_e32 v105, 0xffff0000, v96
	v_lshlrev_b32_e32 v96, 16, v97
	v_and_b32_e32 v97, 0xffff0000, v97
	v_pk_add_f32 v[96:97], v[100:101], v[96:97]
	v_pk_add_f32 v[100:101], v[106:107], v[104:105]
	v_lshlrev_b32_e32 v104, 16, v90
	v_and_b32_e32 v105, 0xffff0000, v90
	v_lshlrev_b32_e32 v90, 16, v91
	v_and_b32_e32 v91, 0xffff0000, v91
	v_pk_add_f32 v[90:91], v[94:95], v[90:91]
	v_lshlrev_b32_e32 v94, 16, v92
	v_and_b32_e32 v95, 0xffff0000, v92
	v_lshlrev_b32_e32 v92, 16, v93
	v_and_b32_e32 v93, 0xffff0000, v93
	v_pk_add_f32 v[98:99], v[98:99], v[104:105]
	v_pk_add_f32 v[92:93], v[96:97], v[92:93]
	v_lshlrev_b32_e32 v96, 16, v86
	v_and_b32_e32 v97, 0xffff0000, v86
	v_lshlrev_b32_e32 v86, 16, v87
	v_and_b32_e32 v87, 0xffff0000, v87
	v_pk_add_f32 v[94:95], v[100:101], v[94:95]
	v_pk_add_f32 v[86:87], v[90:91], v[86:87]
	v_pk_add_f32 v[90:91], v[98:99], v[96:97]
	v_lshlrev_b32_e32 v96, 16, v88
	v_and_b32_e32 v97, 0xffff0000, v88
	v_lshlrev_b32_e32 v88, 16, v89
	v_and_b32_e32 v89, 0xffff0000, v89
	v_pk_add_f32 v[88:89], v[92:93], v[88:89]
	v_pk_add_f32 v[92:93], v[94:95], v[96:97]
	v_lshlrev_b32_e32 v94, 16, v82
	v_and_b32_e32 v95, 0xffff0000, v82
	v_lshlrev_b32_e32 v82, 16, v83
	v_and_b32_e32 v83, 0xffff0000, v83
	v_pk_add_f32 v[82:83], v[86:87], v[82:83]
	v_lshlrev_b32_e32 v86, 16, v84
	v_and_b32_e32 v87, 0xffff0000, v84
	v_lshlrev_b32_e32 v84, 16, v85
	v_and_b32_e32 v85, 0xffff0000, v85
	v_pk_add_f32 v[90:91], v[90:91], v[94:95]
	v_pk_add_f32 v[84:85], v[88:89], v[84:85]
	v_lshlrev_b32_e32 v88, 16, v78
	v_and_b32_e32 v89, 0xffff0000, v78
	v_lshlrev_b32_e32 v78, 16, v79
	v_and_b32_e32 v79, 0xffff0000, v79
	v_pk_add_f32 v[86:87], v[92:93], v[86:87]
	v_pk_add_f32 v[78:79], v[82:83], v[78:79]
	v_pk_add_f32 v[82:83], v[90:91], v[88:89]
	v_lshlrev_b32_e32 v88, 16, v80
	v_and_b32_e32 v89, 0xffff0000, v80
	v_lshlrev_b32_e32 v80, 16, v81
	v_and_b32_e32 v81, 0xffff0000, v81
	v_pk_add_f32 v[80:81], v[84:85], v[80:81]
	v_pk_add_f32 v[84:85], v[86:87], v[88:89]
	v_lshlrev_b32_e32 v86, 16, v74
	v_and_b32_e32 v87, 0xffff0000, v74
	v_lshlrev_b32_e32 v74, 16, v75
	v_and_b32_e32 v75, 0xffff0000, v75
	v_pk_add_f32 v[74:75], v[78:79], v[74:75]
	v_lshlrev_b32_e32 v78, 16, v76
	v_and_b32_e32 v79, 0xffff0000, v76
	v_lshlrev_b32_e32 v76, 16, v77
	v_and_b32_e32 v77, 0xffff0000, v77
	v_pk_add_f32 v[78:79], v[84:85], v[78:79]
	s_waitcnt vmcnt(1)
	v_lshlrev_b32_e32 v84, 16, v70
	v_and_b32_e32 v85, 0xffff0000, v70
	v_lshlrev_b32_e32 v70, 16, v71
	v_and_b32_e32 v71, 0xffff0000, v71
	v_pk_add_f32 v[82:83], v[82:83], v[86:87]
	v_pk_add_f32 v[80:81], v[80:81], v[76:77]
	v_pk_add_f32 v[76:77], v[74:75], v[70:71]
	v_lshlrev_b32_e32 v70, 16, v72
	v_and_b32_e32 v71, 0xffff0000, v72
	v_lshlrev_b32_e32 v72, 16, v73
	v_and_b32_e32 v73, 0xffff0000, v73
	v_pk_add_f32 v[74:75], v[82:83], v[84:85]
	v_pk_add_f32 v[72:73], v[80:81], v[72:73]
	v_pk_add_f32 v[70:71], v[78:79], v[70:71]

.LBB0_1113:
	s_cmpk_gt_i32 s60, 0xff
	s_mov_b64 s[34:35], -1
	s_cbranch_scc0 .LBB0_1157
	s_add_i32 s34, s60, 0xffffff00
	s_and_b32 s35, s60, 3
	v_readfirstlane_b32 s36, v143
	s_and_b32 s67, s34, -4
	s_lshl_b32 s34, s34, 5
	s_lshr_b32 s61, s36, 6
	s_lshl_b32 s36, s35, 3
	v_add_u32_e32 v2, s67, v21
	v_mov_b32_e32 v3, v19
	s_and_b32 s76, s34, 0x7fffff80
	s_add_i32 s61, s61, s36
	v_lshlrev_b64 v[38:39], 12, v[2:3]
	v_or_b32_e32 v10, s76, v29
	v_mov_b32_e32 v11, v19
	v_readlane_b32 s80, v242, 31
	v_lshl_add_u64 v[2:3], s[50:51], 0, v[38:39]
	s_lshl_b32 s62, s61, 7
	v_lshlrev_b64 v[10:11], 10, v[10:11]
	v_readlane_b32 s86, v242, 37
	v_readlane_b32 s87, v242, 38
	v_lshl_add_u64 v[2:3], v[2:3], 0, s[62:63]
	s_lshl_b32 s62, s35, 8
	v_lshl_add_u64 v[10:11], s[86:87], 0, v[10:11]
	v_lshl_add_u64 v[10:11], v[10:11], 0, s[62:63]
	v_mov_b32_e32 v37, v19
	v_lshl_add_u64 v[2:3], v[2:3], 0, v[18:19]
	v_lshl_add_u64 v[14:15], v[10:11], 0, v[36:37]
	global_load_dwordx4 v[6:9], v[2:3], off nt
	s_nop 0
	global_load_dwordx4 v[2:5], v[2:3], off offset:64 nt
	s_barrier
	v_lshrrev_b32_e32 v88, 3, v143
	v_and_b32_e32 v89, 7, v143
	v_and_b32_e32 v90, 0xff, v143
	v_lshrrev_b32_e32 v91, 8, v143
	v_mul_u32_u24_e32 v92, 0x90, v88
	v_lshl_add_u32 v92, v89, 4, v92
	v_mul_u32_u24_e32 v93, 0x1080, v91
	v_lshl_add_u32 v93, v90, 1, v93
	v_add_u32_e32 v94, 0x4200, v93
	v_add_u32_e32 v95, 0xffffff80, v90
	s_waitcnt vmcnt(0)
	s_cmpk_lt_i32 s60, 0x200
	s_cbranch_scc0 .Lat_setb
	v_cvt_pk_bf16_f32 v160, v160, v161
	v_cvt_pk_bf16_f32 v161, v162, v163
	v_cvt_pk_bf16_f32 v162, v164, v165
	v_cvt_pk_bf16_f32 v163, v166, v167
	v_cvt_pk_bf16_f32 v168, v168, v169
	v_cvt_pk_bf16_f32 v169, v170, v171
	v_cvt_pk_bf16_f32 v170, v172, v173
	v_cvt_pk_bf16_f32 v171, v174, v175
	ds_write_b128 v92, v[160:163]
	ds_write_b128 v92, v[168:171] offset:9216
	v_cmp_gt_u32_e32 vcc, 0x100, v143
	s_and_saveexec_b64 s[36:37], vcc
	ds_write_b128 v92, v[176:179] offset:18432
	s_mov_b64 exec, s[36:37]
	v_cmp_gt_u32_e32 vcc, 0x80, v90
	s_and_saveexec_b64 s[36:37], vcc
	v_cvt_pk_bf16_f32 v180, v180, v181
	v_cvt_pk_bf16_f32 v181, v182, v183
	v_cvt_pk_bf16_f32 v182, v184, v185
	v_cvt_pk_bf16_f32 v183, v186, v187
	v_cvt_pk_bf16_f32 v188, v188, v189
	v_cvt_pk_bf16_f32 v189, v190, v191
	v_cvt_pk_bf16_f32 v190, v192, v193
	v_cvt_pk_bf16_f32 v191, v194, v195
	v_cvt_pk_bf16_f32 v196, v196, v197
	v_cvt_pk_bf16_f32 v197, v198, v199
	v_cvt_pk_bf16_f32 v198, v200, v201
	v_cvt_pk_bf16_f32 v199, v202, v203
	v_cvt_pk_bf16_f32 v204, v204, v205
	v_cvt_pk_bf16_f32 v205, v206, v207
	v_cvt_pk_bf16_f32 v206, v208, v209
	v_cvt_pk_bf16_f32 v207, v210, v211
	s_mov_b64 exec, s[36:37]
	v_cmp_gt_u32_e32 vcc, 0xa0, v90
	s_and_saveexec_b64 s[36:37], vcc
	ds_write_b16 v93, v180 offset:36864
	ds_write_b16_d16_hi v93, v180 offset:37392
	ds_write_b16 v93, v181 offset:37920
	ds_write_b16_d16_hi v93, v181 offset:38448
	ds_write_b16 v93, v182 offset:38976
	ds_write_b16_d16_hi v93, v182 offset:39504
	ds_write_b16 v93, v183 offset:40032
	ds_write_b16_d16_hi v93, v183 offset:40560
	ds_write_b16 v93, v188 offset:45312
	ds_write_b16_d16_hi v93, v188 offset:45840
	ds_write_b16 v93, v189 offset:46368
	ds_write_b16_d16_hi v93, v189 offset:46896
	ds_write_b16 v93, v190 offset:47424
	ds_write_b16_d16_hi v93, v190 offset:47952
	ds_write_b16 v93, v191 offset:48480
	ds_write_b16_d16_hi v93, v191 offset:49008
	ds_write_b16 v94, v196 offset:36864
	ds_write_b16_d16_hi v94, v196 offset:37392
	ds_write_b16 v94, v197 offset:37920
	ds_write_b16_d16_hi v94, v197 offset:38448
	ds_write_b16 v94, v198 offset:38976
	ds_write_b16_d16_hi v94, v198 offset:39504
	ds_write_b16 v94, v199 offset:40032
	ds_write_b16_d16_hi v94, v199 offset:40560
	ds_write_b16 v94, v204 offset:45312
	ds_write_b16_d16_hi v94, v204 offset:45840
	ds_write_b16 v94, v205 offset:46368
	ds_write_b16_d16_hi v94, v205 offset:46896
	ds_write_b16 v94, v206 offset:47424
	ds_write_b16_d16_hi v94, v206 offset:47952
	ds_write_b16 v94, v207 offset:48480
	ds_write_b16_d16_hi v94, v207 offset:49008
	s_mov_b64 exec, s[36:37]
	s_branch .Lat_sdone

.LBB0_1157:
	s_and_b64 vcc, exec, s[34:35]
	s_cbranch_vccz .LBB0_1112
	s_bfe_u32 s34, s60, 0x20004
	v_readfirstlane_b32 s35, v143
	s_lshr_b32 s67, s35, 6
	s_lshl_b32 s35, s34, 3
	s_and_b32 s61, s60, 15
	s_add_i32 s67, s67, s35
	s_lshl_b32 s35, s60, 5
	s_and_b32 s35, s35, 0xfffff800
	s_lshl_b32 s36, s61, 7
	s_or_b32 s66, s36, s35
	v_or_b32_e32 v2, s66, v1
	v_ashrrev_i32_e32 v3, 31, v2
	v_lshlrev_b64 v[2:3], 12, v[2:3]
	v_lshl_add_u64 v[2:3], s[50:51], 0, v[2:3]
	s_lshl_b32 s62, s67, 7
	v_lshl_add_u64 v[2:3], v[2:3], 0, s[62:63]
	v_lshl_add_u64 v[2:3], v[2:3], 0, v[18:19]
	global_load_dwordx4 v[14:17], v[2:3], off nt
	global_load_dwordx4 v[10:13], v[2:3], off offset:64 nt
	s_lshl_b32 s76, s34, 6
	s_cmp_lg_u32 s61, 0
	s_cselect_b64 s[78:79], -1, 0
	s_addk_i32 s66, 0xff80
	s_cmp_eq_u32 s61, 0
	v_lshlrev_b32_e32 v38, 1, v20
	s_waitcnt lgkmcnt(0)
	s_barrier
	v_lshrrev_b32_e32 v88, 3, v143
	v_and_b32_e32 v89, 7, v143
	v_and_b32_e32 v90, 0xff, v143
	v_lshrrev_b32_e32 v91, 8, v143
	v_mul_u32_u24_e32 v92, 0x90, v88
	v_lshl_add_u32 v92, v89, 4, v92
	v_mul_u32_u24_e32 v93, 0x1080, v91
	v_lshl_add_u32 v93, v90, 1, v93
	v_add_u32_e32 v94, 0x4200, v93
	v_add_u32_e32 v95, 0xffffff80, v90
	s_lshl_b32 s62, s76, 1
	v_add_u32_e32 v96, s66, v88
	v_lshlrev_b32_e32 v96, 9, v96
	v_lshl_add_u32 v101, v89, 4, s62
	v_add_u32_e32 v96, v96, v101
	v_add_u32_e32 v97, 0x8000, v96
	v_add_u32_e32 v98, 0x10000, v96
	v_add_u32_e32 v99, 0x18000, v96
	v_add_u32_e32 v100, s66, v90
	v_lshlrev_b32_e32 v100, 9, v100
	v_lshl_add_u32 v101, v91, 4, s62
	v_add_u32_e32 v100, v100, v101
	s_cmp_eq_u32 s61, 0
	s_cbranch_scc1 .Lat_pfirst
	global_load_dwordx4 v[56:59], v96, s[48:49]
	global_load_dwordx4 v[60:63], v97, s[48:49]
	global_load_dwordx4 v[64:67], v98, s[48:49]
	global_load_dwordx4 v[68:71], v99, s[48:49]
	global_load_dwordx4 v[72:75], v100, s[54:55]
	global_load_dwordx4 v[76:79], v100, s[54:55] offset:32
	global_load_dwordx4 v[80:83], v100, s[54:55] offset:64
	global_load_dwordx4 v[84:87], v100, s[54:55] offset:96
	s_branch .Lat_pissued

.LBB0_1177:
	v_add_u32_e32 v40, s66, v57
	v_ashrrev_i32_e32 v41, 31, v40
	s_cmp_gt_u32 s34, 6
	v_lshlrev_b64 v[40:41], 12, v[40:41]
	s_cbranch_scc1 .LBB0_1176
	v_lshl_add_u64 v[2:3], s[50:51], 0, v[40:41]
	v_lshl_add_u64 v[2:3], v[2:3], 0, s[62:63]
	v_lshl_add_u64 v[2:3], v[2:3], 0, v[18:19]
	s_mov_b64 s[36:37], 0x10000
	v_lshl_add_u64 v[4:5], v[2:3], 0, s[36:37]
	v_add_co_u32_e32 v2, vcc, 0x10000, v2
	s_nop 1
	v_addc_co_u32_e32 v3, vcc, 0, v3, vcc
	global_load_dwordx4 v[6:9], v[2:3], off nt
	s_nop 0
	global_load_dwordx4 v[2:5], v[4:5], off offset:64 nt
	s_branch .LBB0_1176

.LBB0_1262:
	v_lshl_add_u32 v148, s8, 8, v1
	v_lshl_or_b32 v146, s55, 8, v151
	s_mov_b64 s[36:37], -1
	s_cmp_gt_i32 s81, -1
	v_cvt_pk_bf16_f32 v66, v66, v67
	v_cvt_pk_bf16_f32 v67, v68, v69
	v_cvt_pk_bf16_f32 v68, v126, v127
	v_cvt_pk_bf16_f32 v69, v128, v129
	v_cvt_pk_bf16_f32 v62, v62, v63
	v_cvt_pk_bf16_f32 v63, v64, v65
	v_cvt_pk_bf16_f32 v64, v58, v59
	v_cvt_pk_bf16_f32 v65, v60, v61
	v_cvt_pk_bf16_f32 v58, v122, v123
	v_cvt_pk_bf16_f32 v59, v124, v125
	v_cvt_pk_bf16_f32 v60, v118, v119
	v_cvt_pk_bf16_f32 v61, v120, v121
	v_cvt_pk_bf16_f32 v54, v54, v55
	v_cvt_pk_bf16_f32 v55, v56, v57
	v_cvt_pk_bf16_f32 v56, v50, v51
	v_cvt_pk_bf16_f32 v57, v52, v53
	v_cvt_pk_bf16_f32 v50, v114, v115
	v_cvt_pk_bf16_f32 v51, v116, v117
	v_cvt_pk_bf16_f32 v52, v110, v111
	v_cvt_pk_bf16_f32 v53, v112, v113
	v_cvt_pk_bf16_f32 v46, v46, v47
	v_cvt_pk_bf16_f32 v47, v48, v49
	v_cvt_pk_bf16_f32 v48, v42, v43
	v_cvt_pk_bf16_f32 v49, v44, v45
	v_cvt_pk_bf16_f32 v42, v106, v107
	v_cvt_pk_bf16_f32 v43, v108, v109
	v_cvt_pk_bf16_f32 v44, v102, v103
	v_cvt_pk_bf16_f32 v45, v104, v105
	v_cvt_pk_bf16_f32 v38, v38, v39
	v_cvt_pk_bf16_f32 v39, v40, v41
	v_cvt_pk_bf16_f32 v40, v98, v99
	v_cvt_pk_bf16_f32 v41, v100, v101
	v_cvt_pk_bf16_f32 v34, v34, v35
	v_cvt_pk_bf16_f32 v35, v36, v37
	v_cvt_pk_bf16_f32 v36, v94, v95
	v_cvt_pk_bf16_f32 v37, v96, v97
	v_cvt_pk_bf16_f32 v30, v30, v31
	v_cvt_pk_bf16_f32 v31, v32, v33
	v_cvt_pk_bf16_f32 v32, v26, v27
	v_cvt_pk_bf16_f32 v33, v28, v29
	v_cvt_pk_bf16_f32 v26, v90, v91
	v_cvt_pk_bf16_f32 v27, v92, v93
	v_cvt_pk_bf16_f32 v28, v86, v87
	v_cvt_pk_bf16_f32 v29, v88, v89
	v_cvt_pk_bf16_f32 v22, v22, v23
	v_cvt_pk_bf16_f32 v23, v24, v25
	v_cvt_pk_bf16_f32 v24, v18, v19
	v_cvt_pk_bf16_f32 v25, v20, v21
	v_cvt_pk_bf16_f32 v18, v82, v83
	v_cvt_pk_bf16_f32 v19, v84, v85
	v_cvt_pk_bf16_f32 v20, v78, v79
	v_cvt_pk_bf16_f32 v21, v80, v81
	v_cvt_pk_bf16_f32 v14, v14, v15
	v_cvt_pk_bf16_f32 v15, v16, v17
	v_cvt_pk_bf16_f32 v16, v10, v11
	v_cvt_pk_bf16_f32 v17, v12, v13
	v_cvt_pk_bf16_f32 v10, v74, v75
	v_cvt_pk_bf16_f32 v11, v76, v77
	v_cvt_pk_bf16_f32 v12, v70, v71
	v_cvt_pk_bf16_f32 v13, v72, v73
	s_cbranch_scc0 .LBB0_1276
	s_lshl_b32 s36, s56, 3
	s_add_i32 s48, s36, s81
	s_ashr_i32 s49, s48, 31
	s_lshl_b64 s[48:49], s[48:49], 17
	v_lshl_add_u64 v[74:75], v[138:139], 0, s[48:49]
	s_movk_i32 s8, 0x2000
	v_add_co_u32_e32 v70, vcc, s8, v74
	s_movk_i32 s8, 0x4000
	s_nop 0
	v_addc_co_u32_e32 v71, vcc, 0, v75, vcc
	global_store_dwordx4 v[70:71], v[62:65], off nt
	v_add_co_u32_e32 v70, vcc, s8, v74
	s_movk_i32 s8, 0x6000
	s_nop 0
	v_addc_co_u32_e32 v71, vcc, 0, v75, vcc
	global_store_dwordx4 v[70:71], v[58:61], off nt
	v_add_co_u32_e32 v70, vcc, s8, v74
	s_mov_b32 s8, 0x8000
	s_nop 0
	v_addc_co_u32_e32 v71, vcc, 0, v75, vcc
	global_store_dwordx4 v[70:71], v[54:57], off nt
	v_add_co_u32_e32 v70, vcc, s8, v74
	s_mov_b32 s8, 0xa000
	s_nop 0
	v_addc_co_u32_e32 v71, vcc, 0, v75, vcc
	global_store_dwordx4 v[70:71], v[50:53], off nt
	v_add_co_u32_e32 v70, vcc, s8, v74
	s_mov_b32 s8, 0xc000
	s_nop 0
	v_addc_co_u32_e32 v71, vcc, 0, v75, vcc
	global_store_dwordx4 v[70:71], v[46:49], off nt
	v_add_co_u32_e32 v70, vcc, s8, v74
	s_mov_b32 s8, 0xe000
	s_nop 0
	v_addc_co_u32_e32 v71, vcc, 0, v75, vcc
	global_store_dwordx4 v[70:71], v[42:45], off nt
	v_add_co_u32_e32 v70, vcc, s8, v74
	s_mov_b32 s8, 0x10000
	s_nop 0
	v_addc_co_u32_e32 v71, vcc, 0, v75, vcc
	global_store_dwordx4 v[70:71], v[38:41], off nt
	v_add_co_u32_e32 v70, vcc, s8, v74
	s_mov_b32 s8, 0x12000
	s_nop 0
	v_addc_co_u32_e32 v71, vcc, 0, v75, vcc
	global_store_dwordx4 v[70:71], v[34:37], off nt
	v_add_co_u32_e32 v70, vcc, s8, v74
	s_mov_b32 s8, 0x14000
	s_nop 0
	v_addc_co_u32_e32 v71, vcc, 0, v75, vcc
	global_store_dwordx4 v[70:71], v[30:33], off nt
	v_add_co_u32_e32 v70, vcc, s8, v74
	s_mov_b32 s8, 0x16000
	s_nop 0
	v_addc_co_u32_e32 v71, vcc, 0, v75, vcc
	global_store_dwordx4 v[70:71], v[26:29], off nt
	v_add_co_u32_e32 v70, vcc, s8, v74
	s_mov_b32 s8, 0x18000
	s_nop 0
	v_addc_co_u32_e32 v71, vcc, 0, v75, vcc
	global_store_dwordx4 v[70:71], v[22:25], off nt
	v_add_co_u32_e32 v70, vcc, s8, v74
	s_mov_b32 s8, 0x1a000
	s_nop 0
	v_addc_co_u32_e32 v71, vcc, 0, v75, vcc
	global_store_dwordx4 v[70:71], v[18:21], off nt
	v_add_co_u32_e32 v70, vcc, s8, v74
	s_mov_b32 s8, 0x1c000
	s_nop 0
	v_addc_co_u32_e32 v71, vcc, 0, v75, vcc
	global_store_dwordx4 v[70:71], v[14:17], off nt
	v_add_co_u32_e32 v70, vcc, s8, v74
	global_store_dwordx4 v[74:75], v[66:69], off nt
	s_nop 0
	v_addc_co_u32_e32 v71, vcc, 0, v75, vcc
	v_add_co_u32_e32 v74, vcc, 0x1e000, v74
	global_store_dwordx4 v[70:71], v[10:13], off nt
	v_cvt_pk_bf16_f32 v70, v6, v7
	v_cvt_pk_bf16_f32 v71, v8, v9
	v_cvt_pk_bf16_f32 v72, v2, v3
	v_cvt_pk_bf16_f32 v73, v4, v5
	v_addc_co_u32_e32 v75, vcc, 0, v75, vcc
	global_store_dwordx4 v[74:75], v[70:73], off nt
	s_waitcnt vmcnt(0)
	s_waitcnt vmcnt(0)
	s_barrier
	s_and_saveexec_b64 s[48:49], s[0:1]
	s_cbranch_execz .LBB0_1275
	s_lshl_b32 s50, s56, 6
	s_mov_b64 s[54:55], exec
	s_ashr_i32 s51, s50, 31
	s_lshl_b64 s[50:51], s[50:51], 2
	buffer_wbl2 sc1
	s_waitcnt vmcnt(0)
	v_mbcnt_lo_u32_b32 v70, s54, 0
	s_add_u32 s50, s60, s50
	v_mbcnt_hi_u32_b32 v70, s55, v70
	s_addc_u32 s51, s61, s51
	v_cmp_eq_u32_e32 vcc, 0, v70
	s_and_saveexec_b64 s[56:57], vcc
	s_cbranch_execz .LBB0_1266
	s_bcnt1_i32_b64 s8, s[54:55]
	v_mov_b32_e32 v70, s8
	global_atomic_add v133, v70, s[50:51]

.LBB0_1275:
	s_or_b64 exec, exec, s[48:49]
	s_ashr_i32 s37, s36, 31
	s_lshl_b64 s[36:37], s[36:37], 17
	s_lshl_b32 s8, s81, 1
	v_lshl_add_u64 v[70:71], v[138:139], 0, s[36:37]
	s_lshl_b64 s[36:37], s[8:9], 13
	v_lshl_add_u64 v[70:71], v[70:71], 0, s[36:37]
	v_add_co_u32_e32 v72, vcc, 0x2000, v70
	s_nop 1
	v_addc_co_u32_e32 v73, vcc, 0, v71, vcc
	s_barrier
	global_load_dwordx4 v[102:105], v[70:71], off nt
	global_load_dwordx4 v[98:101], v[72:73], off nt
	v_add_co_u32_e32 v72, vcc, 0x20000, v70
	s_lshl_b32 s8, s81, 5
	s_nop 0
	v_addc_co_u32_e32 v73, vcc, 0, v71, vcc
	v_add_co_u32_e32 v74, vcc, 0x22000, v70
	s_and_b32 s8, s8, 0x7fffff80
	s_nop 0
	v_addc_co_u32_e32 v75, vcc, 0, v71, vcc
	global_load_dwordx4 v[106:109], v[72:73], off nt
	global_load_dwordx4 v[94:97], v[74:75], off nt
	v_add_co_u32_e32 v72, vcc, 0x40000, v70
	v_add_u32_e32 v147, s8, v148
	s_nop 0
	v_addc_co_u32_e32 v73, vcc, 0, v71, vcc
	v_add_co_u32_e32 v74, vcc, 0x42000, v70
	s_lshl_b32 s8, s81, 4
	s_nop 0
	v_addc_co_u32_e32 v75, vcc, 0, v71, vcc
	global_load_dwordx4 v[110:113], v[72:73], off nt
	global_load_dwordx4 v[90:93], v[74:75], off nt
	v_add_co_u32_e32 v72, vcc, 0x60000, v70
	v_and_or_b32 v160, s8, 48, v147
	s_nop 0
	v_addc_co_u32_e32 v73, vcc, 0, v71, vcc
	v_add_co_u32_e32 v74, vcc, 0x62000, v70
	v_ashrrev_i32_e32 v161, 31, v160
	s_nop 0
	v_addc_co_u32_e32 v75, vcc, 0, v71, vcc
	global_load_dwordx4 v[114:117], v[72:73], off nt
	global_load_dwordx4 v[86:89], v[74:75], off nt
	v_add_co_u32_e32 v72, vcc, 0x80000, v70
	v_ashrrev_i32_e32 v147, 31, v146
	s_nop 0
	v_addc_co_u32_e32 v73, vcc, 0, v71, vcc
	v_add_co_u32_e32 v74, vcc, 0x82000, v70
	s_mov_b64 s[36:37], 0
	s_nop 0
	v_addc_co_u32_e32 v75, vcc, 0, v71, vcc
	global_load_dwordx4 v[118:121], v[72:73], off nt
	global_load_dwordx4 v[82:85], v[74:75], off nt
	v_add_co_u32_e32 v72, vcc, 0xa0000, v70
	s_waitcnt vmcnt(9)
	v_lshlrev_b32_e32 v162, 16, v102
	v_addc_co_u32_e32 v73, vcc, 0, v71, vcc
	v_add_co_u32_e32 v74, vcc, 0xa2000, v70
	v_and_b32_e32 v163, 0xffff0000, v102
	s_nop 0
	v_addc_co_u32_e32 v75, vcc, 0, v71, vcc
	global_load_dwordx4 v[122:125], v[72:73], off nt
	global_load_dwordx4 v[78:81], v[74:75], off nt
	v_add_co_u32_e32 v72, vcc, 0xc0000, v70
	v_lshlrev_b32_e32 v102, 16, v103
	s_nop 0
	v_addc_co_u32_e32 v73, vcc, 0, v71, vcc
	v_add_co_u32_e32 v74, vcc, 0xc2000, v70
	v_and_b32_e32 v103, 0xffff0000, v103
	s_nop 0
	v_addc_co_u32_e32 v75, vcc, 0, v71, vcc
	global_load_dwordx4 v[126:129], v[72:73], off nt
	s_nop 0
	global_load_dwordx4 v[74:77], v[74:75], off nt
	v_add_co_u32_e32 v72, vcc, 0xe0000, v70
	v_pk_add_f32 v[162:163], v[162:163], 0 op_sel_hi:[1,0]
	s_nop 0
	v_addc_co_u32_e32 v73, vcc, 0, v71, vcc
	v_add_co_u32_e32 v70, vcc, 0xe2000, v70
	v_pk_add_f32 v[102:103], v[102:103], 0 op_sel_hi:[1,0]
	s_nop 0
	v_addc_co_u32_e32 v71, vcc, 0, v71, vcc
	global_load_dwordx4 v[156:159], v[72:73], off nt
	s_nop 0
	global_load_dwordx4 v[70:73], v[70:71], off nt
	v_lshlrev_b32_e32 v164, 16, v104
	v_and_b32_e32 v165, 0xffff0000, v104
	v_lshlrev_b32_e32 v104, 16, v105
	v_and_b32_e32 v105, 0xffff0000, v105
	s_waitcnt vmcnt(13)
	v_lshlrev_b32_e32 v166, 16, v106
	v_and_b32_e32 v167, 0xffff0000, v106
	v_lshlrev_b32_e32 v106, 16, v107
	v_and_b32_e32 v107, 0xffff0000, v107
	v_pk_add_f32 v[164:165], v[164:165], 0 op_sel_hi:[1,0]
	v_pk_add_f32 v[104:105], v[104:105], 0 op_sel_hi:[1,0]
	v_pk_add_f32 v[102:103], v[102:103], v[106:107]
	v_pk_add_f32 v[106:107], v[162:163], v[166:167]
	v_lshlrev_b32_e32 v162, 16, v108
	v_and_b32_e32 v163, 0xffff0000, v108
	v_lshlrev_b32_e32 v108, 16, v109
	v_and_b32_e32 v109, 0xffff0000, v109
	v_pk_add_f32 v[104:105], v[104:105], v[108:109]
	v_pk_add_f32 v[108:109], v[164:165], v[162:163]
	s_waitcnt vmcnt(11)
	v_lshlrev_b32_e32 v162, 16, v110
	v_and_b32_e32 v163, 0xffff0000, v110
	v_lshlrev_b32_e32 v110, 16, v111
	v_and_b32_e32 v111, 0xffff0000, v111
	v_pk_add_f32 v[102:103], v[102:103], v[110:111]
	v_lshlrev_b32_e32 v110, 16, v112
	v_and_b32_e32 v111, 0xffff0000, v112
	v_lshlrev_b32_e32 v112, 16, v113
	v_and_b32_e32 v113, 0xffff0000, v113
	v_pk_add_f32 v[106:107], v[106:107], v[162:163]
	v_pk_add_f32 v[108:109], v[108:109], v[110:111]
	v_pk_add_f32 v[104:105], v[104:105], v[112:113]
	s_waitcnt vmcnt(9)
	v_lshlrev_b32_e32 v110, 16, v114
	v_and_b32_e32 v111, 0xffff0000, v114
	v_lshlrev_b32_e32 v112, 16, v115
	v_and_b32_e32 v113, 0xffff0000, v115
	v_pk_add_f32 v[102:103], v[102:103], v[112:113]
	v_pk_add_f32 v[106:107], v[106:107], v[110:111]
	v_lshlrev_b32_e32 v110, 16, v116
	v_and_b32_e32 v111, 0xffff0000, v116
	v_lshlrev_b32_e32 v112, 16, v117
	v_and_b32_e32 v113, 0xffff0000, v117
	v_pk_add_f32 v[104:105], v[104:105], v[112:113]
	v_pk_add_f32 v[108:109], v[108:109], v[110:111]
	s_waitcnt vmcnt(7)
	v_lshlrev_b32_e32 v110, 16, v118
	v_and_b32_e32 v111, 0xffff0000, v118
	v_lshlrev_b32_e32 v112, 16, v119
	v_and_b32_e32 v113, 0xffff0000, v119
	v_pk_add_f32 v[106:107], v[106:107], v[110:111]
	v_pk_add_f32 v[102:103], v[102:103], v[112:113]
	v_lshlrev_b32_e32 v110, 16, v120
	v_and_b32_e32 v111, 0xffff0000, v120
	v_lshlrev_b32_e32 v112, 16, v121
	v_and_b32_e32 v113, 0xffff0000, v121
	v_pk_add_f32 v[108:109], v[108:109], v[110:111]
	v_pk_add_f32 v[104:105], v[104:105], v[112:113]
	s_waitcnt vmcnt(5)
	v_lshlrev_b32_e32 v110, 16, v122
	v_and_b32_e32 v111, 0xffff0000, v122
	v_lshlrev_b32_e32 v112, 16, v123
	v_and_b32_e32 v113, 0xffff0000, v123
	v_pk_add_f32 v[102:103], v[102:103], v[112:113]
	v_pk_add_f32 v[106:107], v[106:107], v[110:111]
	v_lshlrev_b32_e32 v110, 16, v124
	v_and_b32_e32 v111, 0xffff0000, v124
	v_lshlrev_b32_e32 v112, 16, v125
	v_and_b32_e32 v113, 0xffff0000, v125
	v_pk_add_f32 v[104:105], v[104:105], v[112:113]
	v_pk_add_f32 v[108:109], v[108:109], v[110:111]
	s_waitcnt vmcnt(3)
	v_lshlrev_b32_e32 v110, 16, v126
	v_and_b32_e32 v111, 0xffff0000, v126
	v_lshlrev_b32_e32 v112, 16, v127
	v_and_b32_e32 v113, 0xffff0000, v127
	v_pk_add_f32 v[106:107], v[106:107], v[110:111]
	v_pk_add_f32 v[102:103], v[102:103], v[112:113]
	v_lshlrev_b32_e32 v110, 16, v128
	v_and_b32_e32 v111, 0xffff0000, v128
	v_lshlrev_b32_e32 v112, 16, v129
	v_and_b32_e32 v113, 0xffff0000, v129
	v_pk_add_f32 v[108:109], v[108:109], v[110:111]
	v_pk_add_f32 v[104:105], v[104:105], v[112:113]
	s_waitcnt vmcnt(1)
	v_lshlrev_b32_e32 v110, 16, v156
	v_and_b32_e32 v111, 0xffff0000, v156
	v_lshlrev_b32_e32 v112, 16, v157
	v_and_b32_e32 v113, 0xffff0000, v157
	v_pk_add_f32 v[102:103], v[102:103], v[112:113]
	v_pk_add_f32 v[106:107], v[106:107], v[110:111]
	v_lshlrev_b32_e32 v110, 16, v158
	v_and_b32_e32 v111, 0xffff0000, v158
	v_lshlrev_b32_e32 v112, 16, v159
	v_and_b32_e32 v113, 0xffff0000, v159
	v_pk_add_f32 v[112:113], v[104:105], v[112:113]
	v_pk_add_f32 v[108:109], v[108:109], v[110:111]
	v_cvt_pk_bf16_f32 v105, v102, v103
	v_lshlrev_b64 v[102:103], 12, v[160:161]
	v_cvt_pk_bf16_f32 v104, v106, v107
	v_cvt_pk_bf16_f32 v106, v108, v109
	v_lshl_add_u64 v[108:109], s[40:41], 0, v[102:103]
	v_cvt_pk_bf16_f32 v107, v112, v113
	v_lshl_add_u64 v[108:109], v[146:147], 1, v[108:109]
	global_store_dwordx4 v[108:109], v[104:107], off
	v_lshlrev_b32_e32 v108, 16, v94
	v_and_b32_e32 v109, 0xffff0000, v94
	v_lshlrev_b32_e32 v104, 16, v98
	v_and_b32_e32 v105, 0xffff0000, v98
	v_lshlrev_b32_e32 v98, 16, v99
	v_and_b32_e32 v99, 0xffff0000, v99
	v_pk_add_f32 v[104:105], v[104:105], 0 op_sel_hi:[1,0]
	v_pk_add_f32 v[98:99], v[98:99], 0 op_sel_hi:[1,0]
	v_lshlrev_b32_e32 v106, 16, v100
	v_and_b32_e32 v107, 0xffff0000, v100
	v_lshlrev_b32_e32 v100, 16, v101
	v_and_b32_e32 v101, 0xffff0000, v101
	v_lshlrev_b32_e32 v94, 16, v95
	v_and_b32_e32 v95, 0xffff0000, v95
	v_pk_add_f32 v[106:107], v[106:107], 0 op_sel_hi:[1,0]
	v_pk_add_f32 v[100:101], v[100:101], 0 op_sel_hi:[1,0]
	v_pk_add_f32 v[94:95], v[98:99], v[94:95]
	v_pk_add_f32 v[98:99], v[104:105], v[108:109]
	v_lshlrev_b32_e32 v104, 16, v96
	v_and_b32_e32 v105, 0xffff0000, v96
	v_lshlrev_b32_e32 v96, 16, v97
	v_and_b32_e32 v97, 0xffff0000, v97
	v_pk_add_f32 v[96:97], v[100:101], v[96:97]
	v_pk_add_f32 v[100:101], v[106:107], v[104:105]
	v_lshlrev_b32_e32 v104, 16, v90
	v_and_b32_e32 v105, 0xffff0000, v90
	v_lshlrev_b32_e32 v90, 16, v91
	v_and_b32_e32 v91, 0xffff0000, v91
	v_pk_add_f32 v[90:91], v[94:95], v[90:91]
	v_lshlrev_b32_e32 v94, 16, v92
	v_and_b32_e32 v95, 0xffff0000, v92
	v_lshlrev_b32_e32 v92, 16, v93
	v_and_b32_e32 v93, 0xffff0000, v93
	v_pk_add_f32 v[98:99], v[98:99], v[104:105]
	v_pk_add_f32 v[92:93], v[96:97], v[92:93]
	v_lshlrev_b32_e32 v96, 16, v86
	v_and_b32_e32 v97, 0xffff0000, v86
	v_lshlrev_b32_e32 v86, 16, v87
	v_and_b32_e32 v87, 0xffff0000, v87
	v_pk_add_f32 v[94:95], v[100:101], v[94:95]
	v_pk_add_f32 v[86:87], v[90:91], v[86:87]
	v_pk_add_f32 v[90:91], v[98:99], v[96:97]
	v_lshlrev_b32_e32 v96, 16, v88
	v_and_b32_e32 v97, 0xffff0000, v88
	v_lshlrev_b32_e32 v88, 16, v89
	v_and_b32_e32 v89, 0xffff0000, v89
	v_pk_add_f32 v[88:89], v[92:93], v[88:89]
	v_pk_add_f32 v[92:93], v[94:95], v[96:97]
	v_lshlrev_b32_e32 v94, 16, v82
	v_and_b32_e32 v95, 0xffff0000, v82
	v_lshlrev_b32_e32 v82, 16, v83
	v_and_b32_e32 v83, 0xffff0000, v83
	v_pk_add_f32 v[82:83], v[86:87], v[82:83]
	v_lshlrev_b32_e32 v86, 16, v84
	v_and_b32_e32 v87, 0xffff0000, v84
	v_lshlrev_b32_e32 v84, 16, v85
	v_and_b32_e32 v85, 0xffff0000, v85
	v_pk_add_f32 v[90:91], v[90:91], v[94:95]
	v_pk_add_f32 v[84:85], v[88:89], v[84:85]
	v_lshlrev_b32_e32 v88, 16, v78
	v_and_b32_e32 v89, 0xffff0000, v78
	v_lshlrev_b32_e32 v78, 16, v79
	v_and_b32_e32 v79, 0xffff0000, v79
	v_pk_add_f32 v[86:87], v[92:93], v[86:87]
	v_pk_add_f32 v[78:79], v[82:83], v[78:79]
	v_pk_add_f32 v[82:83], v[90:91], v[88:89]
	v_lshlrev_b32_e32 v88, 16, v80
	v_and_b32_e32 v89, 0xffff0000, v80
	v_lshlrev_b32_e32 v80, 16, v81
	v_and_b32_e32 v81, 0xffff0000, v81
	v_pk_add_f32 v[80:81], v[84:85], v[80:81]
	v_pk_add_f32 v[84:85], v[86:87], v[88:89]
	v_lshlrev_b32_e32 v86, 16, v74
	v_and_b32_e32 v87, 0xffff0000, v74
	v_lshlrev_b32_e32 v74, 16, v75
	v_and_b32_e32 v75, 0xffff0000, v75
	v_pk_add_f32 v[74:75], v[78:79], v[74:75]
	v_lshlrev_b32_e32 v78, 16, v76
	v_and_b32_e32 v79, 0xffff0000, v76
	v_lshlrev_b32_e32 v76, 16, v77
	v_and_b32_e32 v77, 0xffff0000, v77
	v_pk_add_f32 v[78:79], v[84:85], v[78:79]
	s_waitcnt vmcnt(1)
	v_lshlrev_b32_e32 v84, 16, v70
	v_and_b32_e32 v85, 0xffff0000, v70
	v_lshlrev_b32_e32 v70, 16, v71
	v_and_b32_e32 v71, 0xffff0000, v71
	v_pk_add_f32 v[82:83], v[82:83], v[86:87]
	v_pk_add_f32 v[80:81], v[80:81], v[76:77]
	v_pk_add_f32 v[76:77], v[74:75], v[70:71]
	v_lshlrev_b32_e32 v70, 16, v72
	v_and_b32_e32 v71, 0xffff0000, v72
	v_lshlrev_b32_e32 v72, 16, v73
	v_and_b32_e32 v73, 0xffff0000, v73
	v_pk_add_f32 v[74:75], v[82:83], v[84:85]
	v_pk_add_f32 v[72:73], v[80:81], v[72:73]
	v_pk_add_f32 v[70:71], v[78:79], v[70:71]

.LBB0_1518:
	v_lshl_add_u32 v148, s42, 8, v1
	v_lshl_or_b32 v146, s43, 8, v151
	s_mov_b64 s[30:31], -1
	s_cmp_gt_i32 s88, -1
	v_cvt_pk_bf16_f32 v66, v66, v67
	v_cvt_pk_bf16_f32 v67, v68, v69
	v_cvt_pk_bf16_f32 v68, v126, v127
	v_cvt_pk_bf16_f32 v69, v128, v129
	v_cvt_pk_bf16_f32 v62, v62, v63
	v_cvt_pk_bf16_f32 v63, v64, v65
	v_cvt_pk_bf16_f32 v64, v58, v59
	v_cvt_pk_bf16_f32 v65, v60, v61
	v_cvt_pk_bf16_f32 v58, v122, v123
	v_cvt_pk_bf16_f32 v59, v124, v125
	v_cvt_pk_bf16_f32 v60, v118, v119
	v_cvt_pk_bf16_f32 v61, v120, v121
	v_cvt_pk_bf16_f32 v54, v54, v55
	v_cvt_pk_bf16_f32 v55, v56, v57
	v_cvt_pk_bf16_f32 v56, v50, v51
	v_cvt_pk_bf16_f32 v57, v52, v53
	v_cvt_pk_bf16_f32 v50, v114, v115
	v_cvt_pk_bf16_f32 v51, v116, v117
	v_cvt_pk_bf16_f32 v52, v110, v111
	v_cvt_pk_bf16_f32 v53, v112, v113
	v_cvt_pk_bf16_f32 v46, v46, v47
	v_cvt_pk_bf16_f32 v47, v48, v49
	v_cvt_pk_bf16_f32 v48, v42, v43
	v_cvt_pk_bf16_f32 v49, v44, v45
	v_cvt_pk_bf16_f32 v42, v106, v107
	v_cvt_pk_bf16_f32 v43, v108, v109
	v_cvt_pk_bf16_f32 v44, v102, v103
	v_cvt_pk_bf16_f32 v45, v104, v105
	v_cvt_pk_bf16_f32 v38, v38, v39
	v_cvt_pk_bf16_f32 v39, v40, v41
	v_cvt_pk_bf16_f32 v40, v98, v99
	v_cvt_pk_bf16_f32 v41, v100, v101
	v_cvt_pk_bf16_f32 v34, v34, v35
	v_cvt_pk_bf16_f32 v35, v36, v37
	v_cvt_pk_bf16_f32 v36, v94, v95
	v_cvt_pk_bf16_f32 v37, v96, v97
	v_cvt_pk_bf16_f32 v30, v30, v31
	v_cvt_pk_bf16_f32 v31, v32, v33
	v_cvt_pk_bf16_f32 v32, v26, v27
	v_cvt_pk_bf16_f32 v33, v28, v29
	v_cvt_pk_bf16_f32 v26, v90, v91
	v_cvt_pk_bf16_f32 v27, v92, v93
	v_cvt_pk_bf16_f32 v28, v86, v87
	v_cvt_pk_bf16_f32 v29, v88, v89
	v_cvt_pk_bf16_f32 v22, v22, v23
	v_cvt_pk_bf16_f32 v23, v24, v25
	v_cvt_pk_bf16_f32 v24, v18, v19
	v_cvt_pk_bf16_f32 v25, v20, v21
	v_cvt_pk_bf16_f32 v18, v82, v83
	v_cvt_pk_bf16_f32 v19, v84, v85
	v_cvt_pk_bf16_f32 v20, v78, v79
	v_cvt_pk_bf16_f32 v21, v80, v81
	v_cvt_pk_bf16_f32 v14, v14, v15
	v_cvt_pk_bf16_f32 v15, v16, v17
	v_cvt_pk_bf16_f32 v16, v10, v11
	v_cvt_pk_bf16_f32 v17, v12, v13
	v_cvt_pk_bf16_f32 v10, v74, v75
	v_cvt_pk_bf16_f32 v11, v76, v77
	v_cvt_pk_bf16_f32 v12, v70, v71
	v_cvt_pk_bf16_f32 v13, v72, v73
	s_cbranch_scc0 .LBB0_1532
	s_lshl_b32 s30, s6, 3
	s_add_i32 s34, s30, s88
	s_ashr_i32 s35, s34, 31
	s_lshl_b64 s[34:35], s[34:35], 17
	v_lshl_add_u64 v[74:75], v[138:139], 0, s[34:35]
	s_movk_i32 s17, 0x2000
	v_add_co_u32_e32 v70, vcc, s17, v74
	s_mov_b32 s17, 0x10000
	s_nop 0
	v_addc_co_u32_e32 v71, vcc, 0, v75, vcc
	global_store_dwordx4 v[70:71], v[62:65], off nt
	v_add_co_u32_e32 v70, vcc, s56, v74
	global_store_dwordx4 v[74:75], v[66:69], off nt
	s_nop 0
	v_addc_co_u32_e32 v71, vcc, 0, v75, vcc
	global_store_dwordx4 v[70:71], v[58:61], off nt
	v_add_co_u32_e32 v70, vcc, s57, v74
	v_cvt_pk_bf16_f32 v72, v2, v3
	s_nop 0
	v_addc_co_u32_e32 v71, vcc, 0, v75, vcc
	global_store_dwordx4 v[70:71], v[54:57], off nt
	v_add_co_u32_e32 v70, vcc, s33, v74
	v_cvt_pk_bf16_f32 v73, v4, v5
	s_nop 0
	v_addc_co_u32_e32 v71, vcc, 0, v75, vcc
	global_store_dwordx4 v[70:71], v[50:53], off nt
	v_add_co_u32_e32 v70, vcc, s65, v74
	s_nop 1
	v_addc_co_u32_e32 v71, vcc, 0, v75, vcc
	global_store_dwordx4 v[70:71], v[46:49], off nt
	v_add_co_u32_e32 v70, vcc, s82, v74
	s_nop 1
	v_addc_co_u32_e32 v71, vcc, 0, v75, vcc
	global_store_dwordx4 v[70:71], v[42:45], off nt
	v_add_co_u32_e32 v70, vcc, s83, v74
	s_nop 1
	v_addc_co_u32_e32 v71, vcc, 0, v75, vcc
	global_store_dwordx4 v[70:71], v[38:41], off nt
	v_add_co_u32_e32 v70, vcc, s17, v74
	s_nop 1
	v_addc_co_u32_e32 v71, vcc, 0, v75, vcc
	global_store_dwordx4 v[70:71], v[34:37], off nt
	v_add_co_u32_e32 v70, vcc, s53, v74
	s_nop 1
	v_addc_co_u32_e32 v71, vcc, 0, v75, vcc
	global_store_dwordx4 v[70:71], v[30:33], off nt
	v_add_co_u32_e32 v70, vcc, s54, v74
	s_nop 1
	v_addc_co_u32_e32 v71, vcc, 0, v75, vcc
	global_store_dwordx4 v[70:71], v[26:29], off nt
	v_add_co_u32_e32 v70, vcc, s55, v74
	s_nop 1
	v_addc_co_u32_e32 v71, vcc, 0, v75, vcc
	global_store_dwordx4 v[70:71], v[22:25], off nt
	v_add_co_u32_e32 v70, vcc, s62, v74
	s_nop 1
	v_addc_co_u32_e32 v71, vcc, 0, v75, vcc
	global_store_dwordx4 v[70:71], v[18:21], off nt
	v_add_co_u32_e32 v70, vcc, s63, v74
	s_nop 1
	v_addc_co_u32_e32 v71, vcc, 0, v75, vcc
	global_store_dwordx4 v[70:71], v[14:17], off nt
	v_add_co_u32_e32 v70, vcc, s66, v74
	s_nop 1
	v_addc_co_u32_e32 v71, vcc, 0, v75, vcc
	v_add_co_u32_e32 v74, vcc, 0x1e000, v74
	global_store_dwordx4 v[70:71], v[10:13], off nt
	v_cvt_pk_bf16_f32 v70, v6, v7
	v_cvt_pk_bf16_f32 v71, v8, v9
	v_addc_co_u32_e32 v75, vcc, 0, v75, vcc
	global_store_dwordx4 v[74:75], v[70:73], off nt
	s_waitcnt vmcnt(0)
	s_waitcnt vmcnt(0)
	s_barrier
	s_and_saveexec_b64 s[34:35], s[0:1]
	s_cbranch_execz .LBB0_1531
	s_lshl_b32 s36, s6, 6
	s_mov_b64 s[42:43], exec
	s_ashr_i32 s37, s36, 31
	s_lshl_b64 s[36:37], s[36:37], 2
	buffer_wbl2 sc1
	s_waitcnt vmcnt(0)
	v_mbcnt_lo_u32_b32 v70, s42, 0
	s_add_u32 s36, s58, s36
	v_mbcnt_hi_u32_b32 v70, s43, v70
	s_addc_u32 s37, s59, s37
	v_cmp_eq_u32_e32 vcc, 0, v70
	s_and_saveexec_b64 s[44:45], vcc
	s_cbranch_execz .LBB0_1522
	s_bcnt1_i32_b64 s6, s[42:43]
	v_mov_b32_e32 v70, s6
	global_atomic_add v133, v70, s[36:37]

.LBB0_1531:
	s_or_b64 exec, exec, s[34:35]
	s_ashr_i32 s31, s30, 31
	s_lshl_b64 s[30:31], s[30:31], 17
	s_lshl_b32 s6, s88, 1
	v_lshl_add_u64 v[70:71], v[138:139], 0, s[30:31]
	s_lshl_b64 s[30:31], s[6:7], 13
	v_lshl_add_u64 v[70:71], v[70:71], 0, s[30:31]
	v_add_co_u32_e32 v72, vcc, 0x2000, v70
	s_nop 1
	v_addc_co_u32_e32 v73, vcc, 0, v71, vcc
	s_barrier
	global_load_dwordx4 v[102:105], v[70:71], off nt
	global_load_dwordx4 v[98:101], v[72:73], off nt
	v_add_co_u32_e32 v72, vcc, 0x20000, v70
	s_lshl_b32 s6, s88, 5
	s_nop 0
	v_addc_co_u32_e32 v73, vcc, 0, v71, vcc
	v_add_co_u32_e32 v74, vcc, 0x22000, v70
	s_and_b32 s6, s6, 0x7fffff80
	s_nop 0
	v_addc_co_u32_e32 v75, vcc, 0, v71, vcc
	global_load_dwordx4 v[106:109], v[72:73], off nt
	global_load_dwordx4 v[94:97], v[74:75], off nt
	v_add_co_u32_e32 v72, vcc, 0x40000, v70
	v_add_u32_e32 v147, s6, v148
	s_nop 0
	v_addc_co_u32_e32 v73, vcc, 0, v71, vcc
	v_add_co_u32_e32 v74, vcc, 0x42000, v70
	s_lshl_b32 s6, s88, 4
	s_nop 0
	v_addc_co_u32_e32 v75, vcc, 0, v71, vcc
	global_load_dwordx4 v[110:113], v[72:73], off nt
	global_load_dwordx4 v[90:93], v[74:75], off nt
	v_add_co_u32_e32 v72, vcc, 0x60000, v70
	v_and_or_b32 v160, s6, 48, v147
	s_nop 0
	v_addc_co_u32_e32 v73, vcc, 0, v71, vcc
	v_add_co_u32_e32 v74, vcc, 0x62000, v70
	v_ashrrev_i32_e32 v161, 31, v160
	s_nop 0
	v_addc_co_u32_e32 v75, vcc, 0, v71, vcc
	global_load_dwordx4 v[114:117], v[72:73], off nt
	global_load_dwordx4 v[86:89], v[74:75], off nt
	v_add_co_u32_e32 v72, vcc, 0x80000, v70
	v_ashrrev_i32_e32 v147, 31, v146
	s_nop 0
	v_addc_co_u32_e32 v73, vcc, 0, v71, vcc
	v_add_co_u32_e32 v74, vcc, 0x82000, v70
	s_mov_b64 s[30:31], 0
	s_nop 0
	v_addc_co_u32_e32 v75, vcc, 0, v71, vcc
	global_load_dwordx4 v[118:121], v[72:73], off nt
	global_load_dwordx4 v[82:85], v[74:75], off nt
	v_add_co_u32_e32 v72, vcc, 0xa0000, v70
	s_waitcnt vmcnt(9)
	v_lshlrev_b32_e32 v162, 16, v102
	v_addc_co_u32_e32 v73, vcc, 0, v71, vcc
	v_add_co_u32_e32 v74, vcc, 0xa2000, v70
	v_and_b32_e32 v163, 0xffff0000, v102
	s_nop 0
	v_addc_co_u32_e32 v75, vcc, 0, v71, vcc
	global_load_dwordx4 v[122:125], v[72:73], off nt
	global_load_dwordx4 v[78:81], v[74:75], off nt
	v_add_co_u32_e32 v72, vcc, 0xc0000, v70
	v_lshlrev_b32_e32 v102, 16, v103
	s_nop 0
	v_addc_co_u32_e32 v73, vcc, 0, v71, vcc
	v_add_co_u32_e32 v74, vcc, 0xc2000, v70
	v_and_b32_e32 v103, 0xffff0000, v103
	s_nop 0
	v_addc_co_u32_e32 v75, vcc, 0, v71, vcc
	global_load_dwordx4 v[126:129], v[72:73], off nt
	s_nop 0
	global_load_dwordx4 v[74:77], v[74:75], off nt
	v_add_co_u32_e32 v72, vcc, 0xe0000, v70
	v_pk_add_f32 v[162:163], v[162:163], 0 op_sel_hi:[1,0]
	s_nop 0
	v_addc_co_u32_e32 v73, vcc, 0, v71, vcc
	v_add_co_u32_e32 v70, vcc, 0xe2000, v70
	v_pk_add_f32 v[102:103], v[102:103], 0 op_sel_hi:[1,0]
	s_nop 0
	v_addc_co_u32_e32 v71, vcc, 0, v71, vcc
	global_load_dwordx4 v[156:159], v[72:73], off nt
	s_nop 0
	global_load_dwordx4 v[70:73], v[70:71], off nt
	v_lshlrev_b32_e32 v164, 16, v104
	v_and_b32_e32 v165, 0xffff0000, v104
	v_lshlrev_b32_e32 v104, 16, v105
	v_and_b32_e32 v105, 0xffff0000, v105
	s_waitcnt vmcnt(13)
	v_lshlrev_b32_e32 v166, 16, v106
	v_and_b32_e32 v167, 0xffff0000, v106
	v_lshlrev_b32_e32 v106, 16, v107
	v_and_b32_e32 v107, 0xffff0000, v107
	v_pk_add_f32 v[164:165], v[164:165], 0 op_sel_hi:[1,0]
	v_pk_add_f32 v[104:105], v[104:105], 0 op_sel_hi:[1,0]
	v_pk_add_f32 v[102:103], v[102:103], v[106:107]
	v_pk_add_f32 v[106:107], v[162:163], v[166:167]
	v_lshlrev_b32_e32 v162, 16, v108
	v_and_b32_e32 v163, 0xffff0000, v108
	v_lshlrev_b32_e32 v108, 16, v109
	v_and_b32_e32 v109, 0xffff0000, v109
	v_pk_add_f32 v[104:105], v[104:105], v[108:109]
	v_pk_add_f32 v[108:109], v[164:165], v[162:163]
	s_waitcnt vmcnt(11)
	v_lshlrev_b32_e32 v162, 16, v110
	v_and_b32_e32 v163, 0xffff0000, v110
	v_lshlrev_b32_e32 v110, 16, v111
	v_and_b32_e32 v111, 0xffff0000, v111
	v_pk_add_f32 v[102:103], v[102:103], v[110:111]
	v_lshlrev_b32_e32 v110, 16, v112
	v_and_b32_e32 v111, 0xffff0000, v112
	v_lshlrev_b32_e32 v112, 16, v113
	v_and_b32_e32 v113, 0xffff0000, v113
	v_pk_add_f32 v[106:107], v[106:107], v[162:163]
	v_pk_add_f32 v[108:109], v[108:109], v[110:111]
	v_pk_add_f32 v[104:105], v[104:105], v[112:113]
	s_waitcnt vmcnt(9)
	v_lshlrev_b32_e32 v110, 16, v114
	v_and_b32_e32 v111, 0xffff0000, v114
	v_lshlrev_b32_e32 v112, 16, v115
	v_and_b32_e32 v113, 0xffff0000, v115
	v_pk_add_f32 v[102:103], v[102:103], v[112:113]
	v_pk_add_f32 v[106:107], v[106:107], v[110:111]
	v_lshlrev_b32_e32 v110, 16, v116
	v_and_b32_e32 v111, 0xffff0000, v116
	v_lshlrev_b32_e32 v112, 16, v117
	v_and_b32_e32 v113, 0xffff0000, v117
	v_pk_add_f32 v[104:105], v[104:105], v[112:113]
	v_pk_add_f32 v[108:109], v[108:109], v[110:111]
	s_waitcnt vmcnt(7)
	v_lshlrev_b32_e32 v110, 16, v118
	v_and_b32_e32 v111, 0xffff0000, v118
	v_lshlrev_b32_e32 v112, 16, v119
	v_and_b32_e32 v113, 0xffff0000, v119
	v_pk_add_f32 v[106:107], v[106:107], v[110:111]
	v_pk_add_f32 v[102:103], v[102:103], v[112:113]
	v_lshlrev_b32_e32 v110, 16, v120
	v_and_b32_e32 v111, 0xffff0000, v120
	v_lshlrev_b32_e32 v112, 16, v121
	v_and_b32_e32 v113, 0xffff0000, v121
	v_pk_add_f32 v[108:109], v[108:109], v[110:111]
	v_pk_add_f32 v[104:105], v[104:105], v[112:113]
	s_waitcnt vmcnt(5)
	v_lshlrev_b32_e32 v110, 16, v122
	v_and_b32_e32 v111, 0xffff0000, v122
	v_lshlrev_b32_e32 v112, 16, v123
	v_and_b32_e32 v113, 0xffff0000, v123
	v_pk_add_f32 v[102:103], v[102:103], v[112:113]
	v_pk_add_f32 v[106:107], v[106:107], v[110:111]
	v_lshlrev_b32_e32 v110, 16, v124
	v_and_b32_e32 v111, 0xffff0000, v124
	v_lshlrev_b32_e32 v112, 16, v125
	v_and_b32_e32 v113, 0xffff0000, v125
	v_pk_add_f32 v[104:105], v[104:105], v[112:113]
	v_pk_add_f32 v[108:109], v[108:109], v[110:111]
	s_waitcnt vmcnt(3)
	v_lshlrev_b32_e32 v110, 16, v126
	v_and_b32_e32 v111, 0xffff0000, v126
	v_lshlrev_b32_e32 v112, 16, v127
	v_and_b32_e32 v113, 0xffff0000, v127
	v_pk_add_f32 v[106:107], v[106:107], v[110:111]
	v_pk_add_f32 v[102:103], v[102:103], v[112:113]
	v_lshlrev_b32_e32 v110, 16, v128
	v_and_b32_e32 v111, 0xffff0000, v128
	v_lshlrev_b32_e32 v112, 16, v129
	v_and_b32_e32 v113, 0xffff0000, v129
	v_pk_add_f32 v[108:109], v[108:109], v[110:111]
	v_pk_add_f32 v[104:105], v[104:105], v[112:113]
	s_waitcnt vmcnt(1)
	v_lshlrev_b32_e32 v110, 16, v156
	v_and_b32_e32 v111, 0xffff0000, v156
	v_lshlrev_b32_e32 v112, 16, v157
	v_and_b32_e32 v113, 0xffff0000, v157
	v_pk_add_f32 v[102:103], v[102:103], v[112:113]
	v_pk_add_f32 v[106:107], v[106:107], v[110:111]
	v_lshlrev_b32_e32 v110, 16, v158
	v_and_b32_e32 v111, 0xffff0000, v158
	v_lshlrev_b32_e32 v112, 16, v159
	v_and_b32_e32 v113, 0xffff0000, v159
	v_pk_add_f32 v[112:113], v[104:105], v[112:113]
	v_pk_add_f32 v[108:109], v[108:109], v[110:111]
	v_cvt_pk_bf16_f32 v105, v102, v103
	v_lshlrev_b64 v[102:103], 12, v[160:161]
	v_cvt_pk_bf16_f32 v104, v106, v107
	v_cvt_pk_bf16_f32 v106, v108, v109
	v_lshl_add_u64 v[108:109], s[40:41], 0, v[102:103]
	v_cvt_pk_bf16_f32 v107, v112, v113
	v_lshl_add_u64 v[108:109], v[146:147], 1, v[108:109]
	global_store_dwordx4 v[108:109], v[104:107], off
	v_lshlrev_b32_e32 v108, 16, v94
	v_and_b32_e32 v109, 0xffff0000, v94
	v_lshlrev_b32_e32 v104, 16, v98
	v_and_b32_e32 v105, 0xffff0000, v98
	v_lshlrev_b32_e32 v98, 16, v99
	v_and_b32_e32 v99, 0xffff0000, v99
	v_pk_add_f32 v[104:105], v[104:105], 0 op_sel_hi:[1,0]
	v_pk_add_f32 v[98:99], v[98:99], 0 op_sel_hi:[1,0]
	v_lshlrev_b32_e32 v106, 16, v100
	v_and_b32_e32 v107, 0xffff0000, v100
	v_lshlrev_b32_e32 v100, 16, v101
	v_and_b32_e32 v101, 0xffff0000, v101
	v_lshlrev_b32_e32 v94, 16, v95
	v_and_b32_e32 v95, 0xffff0000, v95
	v_pk_add_f32 v[106:107], v[106:107], 0 op_sel_hi:[1,0]
	v_pk_add_f32 v[100:101], v[100:101], 0 op_sel_hi:[1,0]
	v_pk_add_f32 v[94:95], v[98:99], v[94:95]
	v_pk_add_f32 v[98:99], v[104:105], v[108:109]
	v_lshlrev_b32_e32 v104, 16, v96
	v_and_b32_e32 v105, 0xffff0000, v96
	v_lshlrev_b32_e32 v96, 16, v97
	v_and_b32_e32 v97, 0xffff0000, v97
	v_pk_add_f32 v[96:97], v[100:101], v[96:97]
	v_pk_add_f32 v[100:101], v[106:107], v[104:105]
	v_lshlrev_b32_e32 v104, 16, v90
	v_and_b32_e32 v105, 0xffff0000, v90
	v_lshlrev_b32_e32 v90, 16, v91
	v_and_b32_e32 v91, 0xffff0000, v91
	v_pk_add_f32 v[90:91], v[94:95], v[90:91]
	v_lshlrev_b32_e32 v94, 16, v92
	v_and_b32_e32 v95, 0xffff0000, v92
	v_lshlrev_b32_e32 v92, 16, v93
	v_and_b32_e32 v93, 0xffff0000, v93
	v_pk_add_f32 v[98:99], v[98:99], v[104:105]
	v_pk_add_f32 v[92:93], v[96:97], v[92:93]
	v_lshlrev_b32_e32 v96, 16, v86
	v_and_b32_e32 v97, 0xffff0000, v86
	v_lshlrev_b32_e32 v86, 16, v87
	v_and_b32_e32 v87, 0xffff0000, v87
	v_pk_add_f32 v[94:95], v[100:101], v[94:95]
	v_pk_add_f32 v[86:87], v[90:91], v[86:87]
	v_pk_add_f32 v[90:91], v[98:99], v[96:97]
	v_lshlrev_b32_e32 v96, 16, v88
	v_and_b32_e32 v97, 0xffff0000, v88
	v_lshlrev_b32_e32 v88, 16, v89
	v_and_b32_e32 v89, 0xffff0000, v89
	v_pk_add_f32 v[88:89], v[92:93], v[88:89]
	v_pk_add_f32 v[92:93], v[94:95], v[96:97]
	v_lshlrev_b32_e32 v94, 16, v82
	v_and_b32_e32 v95, 0xffff0000, v82
	v_lshlrev_b32_e32 v82, 16, v83
	v_and_b32_e32 v83, 0xffff0000, v83
	v_pk_add_f32 v[82:83], v[86:87], v[82:83]
	v_lshlrev_b32_e32 v86, 16, v84
	v_and_b32_e32 v87, 0xffff0000, v84
	v_lshlrev_b32_e32 v84, 16, v85
	v_and_b32_e32 v85, 0xffff0000, v85
	v_pk_add_f32 v[90:91], v[90:91], v[94:95]
	v_pk_add_f32 v[84:85], v[88:89], v[84:85]
	v_lshlrev_b32_e32 v88, 16, v78
	v_and_b32_e32 v89, 0xffff0000, v78
	v_lshlrev_b32_e32 v78, 16, v79
	v_and_b32_e32 v79, 0xffff0000, v79
	v_pk_add_f32 v[86:87], v[92:93], v[86:87]
	v_pk_add_f32 v[78:79], v[82:83], v[78:79]
	v_pk_add_f32 v[82:83], v[90:91], v[88:89]
	v_lshlrev_b32_e32 v88, 16, v80
	v_and_b32_e32 v89, 0xffff0000, v80
	v_lshlrev_b32_e32 v80, 16, v81
	v_and_b32_e32 v81, 0xffff0000, v81
	v_pk_add_f32 v[80:81], v[84:85], v[80:81]
	v_pk_add_f32 v[84:85], v[86:87], v[88:89]
	v_lshlrev_b32_e32 v86, 16, v74
	v_and_b32_e32 v87, 0xffff0000, v74
	v_lshlrev_b32_e32 v74, 16, v75
	v_and_b32_e32 v75, 0xffff0000, v75
	v_pk_add_f32 v[74:75], v[78:79], v[74:75]
	v_lshlrev_b32_e32 v78, 16, v76
	v_and_b32_e32 v79, 0xffff0000, v76
	v_lshlrev_b32_e32 v76, 16, v77
	v_and_b32_e32 v77, 0xffff0000, v77
	v_pk_add_f32 v[78:79], v[84:85], v[78:79]
	s_waitcnt vmcnt(1)
	v_lshlrev_b32_e32 v84, 16, v70
	v_and_b32_e32 v85, 0xffff0000, v70
	v_lshlrev_b32_e32 v70, 16, v71
	v_and_b32_e32 v71, 0xffff0000, v71
	v_pk_add_f32 v[82:83], v[82:83], v[86:87]
	v_pk_add_f32 v[80:81], v[80:81], v[76:77]
	v_pk_add_f32 v[76:77], v[74:75], v[70:71]
	v_lshlrev_b32_e32 v70, 16, v72
	v_and_b32_e32 v71, 0xffff0000, v72
	v_lshlrev_b32_e32 v72, 16, v73
	v_and_b32_e32 v73, 0xffff0000, v73
	v_pk_add_f32 v[74:75], v[82:83], v[84:85]
	v_pk_add_f32 v[72:73], v[80:81], v[72:73]
	v_pk_add_f32 v[70:71], v[78:79], v[70:71]
